# v18 + DMA-first loader segments: LDS-DMA pieces issued before the ds_read_b128 fragment reads in each K-loop loader segment
# speedup vs baseline: 1.0014x; 1.0014x over previous
; #define PG8_STAGE(bufoff, gbase, voff) do { _Pragma("unroll") for (int _i = 0; _i < 2; ++_i) \
;         __builtin_amdgcn_global_load_lds((const unsigned*)((const char*)(gbase) + (voff)[_i]), (PG8_LAS unsigned*)(lds + (bufoff) + ldsw + _i * 8192), 16, 0, 0); } while (0)
; #define PG8_LDA(dst, b, h) do { _Pragma("unroll") for (int m = 0; m < 4; ++m) _Pragma("unroll") for (int k = 0; k < 2; ++k) dst[m][k] = *(const PG8_LAS bf16x8*)(lds + PG8_SA(b, h) + aoff + m * 2048 + k * 1024); } while (0)
; #define PG8_LDB(dst, b, h) do { _Pragma("unroll") for (int n = 0; n < 2; ++n) _Pragma("unroll") for (int k = 0; k < 2; ++k) dst[n][k] = *(const PG8_LAS bf16x8*)(lds + PG8_SB(b, h) + boff + n * 2048 + k * 1024); } while (0)
; #define PG8_WAIT_V(n) asm volatile("s_waitcnt vmcnt(" #n ")" ::: "memory")
; #define PG8_WAIT_L(n) asm volatile("s_waitcnt lgkmcnt(" #n ")" ::: "memory")
; #define PG8_BAR __builtin_amdgcn_s_barrier()
; template <class Epi, class Sched, bool ALIGN_EPI = false, bool SP2 = false>
; __device__ __forceinline__ void gemm_phase(PG8_LAS unsigned char* lds, const Gemm g, const Sched& S, const Epi& E) {
;     ...
;         const bool has_next = S.next(ui + 1, nxt);
;         const char* nA = has_next ? (const char*)g.A + (size_t)nxt.pm * tstep + (size_t)nxt.kt0 * kstep : cA; const char* nB = has_next ? (const char*)g.Bt + (size_t)nxt.pn * tstep + (size_t)nxt.kt0 * kstep : cB;
;         const int nt = cur.nt;
;         for (int t = 0; t < nt; t += 2) {
;             const bool last = (t == nt - 2);
;             const char* a1 = cA + (size_t)(t + 1) * kstep;
;             const char* a2 = last ? nA : cA + (size_t)(t + 2) * kstep; const char* b2 = last ? nB : cB + (size_t)(t + 2) * kstep;
;             const char* a3 = a2 + kstep; const char* b3 = b2 + kstep;
;             if (last && has_next) S.a_ready(nxt);
;             if constexpr (SP2) {
;             PG8_LDB(B0, 0, 0); PG8_LDB(B1, 0, 1); PG8_SCHED; PG8_LDA(At, 0, 0); PG8_STAGE(PG8_SA(1, 1), a1 + hstep, voffA);
;             PG8_WAIT_V(8); PG8_WAIT_L(0); PG8_BAR; PG8_MMA(0, 0, At, B0); PG8_MMA(0, 1, At, B1); PG8_BAR; PG8_SCHED;
;             PG8_LDA(At, 0, 1); PG8_STAGE(PG8_SB(0, 0), b2, voffB); PG8_STAGE(PG8_SB(0, 1), b2 + hstep, voffB); PG8_STAGE(PG8_SA(0, 0), a2, voffA);
;             PG8_WAIT_V(8); PG8_WAIT_L(0); PG8_BAR; PG8_MMA(1, 0, At, B0); PG8_MMA(1, 1, At, B1); PG8_BAR; PG8_SCHED;
.LBB0_235:
	s_ashr_i32 s41, s40, 31
	s_lshl_b64 s[42:43], s[40:41], 19
	s_add_u32 s42, s22, s42
	s_addc_u32 s43, s23, s43
	s_and_b64 s[44:45], s[36:37], exec
	s_cselect_b32 s66, s43, s87
	s_cselect_b32 s67, s42, s86
	s_ashr_i32 s39, s38, 31
	s_lshl_b64 s[44:45], s[38:39], 19
	s_add_u32 s44, s11, s44
	s_addc_u32 s45, s12, s45
	s_and_b64 s[68:69], s[36:37], exec
	s_cselect_b32 s39, s45, s89
	s_cselect_b32 s68, s44, s88
	s_add_u32 s86, s86, 0x40080
	s_addc_u32 s87, s87, 0
	s_add_u32 s69, s88, 0x100
	s_addc_u32 s71, s89, 0
	s_mov_b32 s75, -2
	s_waitcnt vmcnt(0)
	s_add_u32 s76, s86, 0xfffc0080
	s_addc_u32 s77, s87, -1
	s_add_i32 s80, 0, 0x10000
	s_cmp_eq_u32 s75, 12
	s_cselect_b32 s91, s66, s77
	s_cselect_b32 s90, s67, s76
	s_cselect_b32 s89, s39, s71
	s_cselect_b32 s88, s68, s69
	s_add_i32 s81, 0, 0x14000
	v_add_u32_e32 v154, s80, v176
	v_add_u32_e32 v186, s81, v176
	ds_read_b128 v[48:51], v154
	ds_read_b128 v[60:63], v154 offset:1024
	ds_read_b128 v[138:141], v154 offset:2048
	ds_read_b128 v[154:157], v154 offset:3072
	ds_read_b128 v[158:161], v186
	ds_read_b128 v[178:181], v186 offset:1024
	ds_read_b128 v[182:185], v186 offset:2048
	ds_read_b128 v[186:189], v186 offset:3072
	v_lshl_add_u64 v[194:195], s[86:87], 0, v[150:151]
	s_add_i32 m0, s15, 0xc000
	ds_read_b128 v[190:193], v177
	ds_read_b128 v[212:215], v177 offset:1024
	ds_read_b128 v[216:219], v177 offset:2048
	ds_read_b128 v[220:223], v177 offset:3072
	ds_read_b128 v[224:227], v177 offset:4096
	ds_read_b128 v[228:231], v177 offset:5120
	ds_read_b128 v[232:235], v177 offset:6144
	ds_read_b128 v[236:239], v177 offset:7168
	global_load_lds_dwordx4 v[194:195], off
	v_lshl_add_u64 v[194:195], s[86:87], 0, v[152:153]
	s_add_i32 m0, s15, 0xe000
	s_nop 0
	global_load_lds_dwordx4 v[194:195], off
	s_waitcnt vmcnt(8)
	s_waitcnt lgkmcnt(0)
	s_barrier
	s_setprio 1
	s_waitcnt lgkmcnt(0)
	v_mfma_f32_16x16x32_bf16 v[134:137], v[48:51], v[190:193], 0
	v_mfma_f32_16x16x32_bf16 v[126:129], v[138:141], v[190:193], 0
	v_mfma_f32_16x16x32_bf16 v[110:113], v[138:141], v[216:219], 0
	v_mfma_f32_16x16x32_bf16 v[118:121], v[48:51], v[216:219], 0
	v_mfma_f32_16x16x32_bf16 v[102:105], v[48:51], v[224:227], 0
	v_mfma_f32_16x16x32_bf16 v[94:97], v[138:141], v[224:227], 0
	v_mfma_f32_16x16x32_bf16 v[76:79], v[138:141], v[232:235], 0
	v_mfma_f32_16x16x32_bf16 v[86:89], v[48:51], v[232:235], 0
	v_mfma_f32_16x16x32_bf16 v[134:137], v[60:63], v[212:215], v[134:137]
	v_mfma_f32_16x16x32_bf16 v[126:129], v[154:157], v[212:215], v[126:129]
	v_mfma_f32_16x16x32_bf16 v[110:113], v[154:157], v[220:223], v[110:113]
	v_mfma_f32_16x16x32_bf16 v[118:121], v[60:63], v[220:223], v[118:121]
	v_mfma_f32_16x16x32_bf16 v[102:105], v[60:63], v[228:231], v[102:105]
	v_mfma_f32_16x16x32_bf16 v[94:97], v[154:157], v[228:231], v[94:97]
	v_mfma_f32_16x16x32_bf16 v[76:79], v[154:157], v[236:239], v[76:79]
	v_mfma_f32_16x16x32_bf16 v[86:89], v[60:63], v[236:239], v[86:89]
	v_mfma_f32_16x16x32_bf16 v[130:133], v[158:161], v[190:193], 0
	v_mfma_f32_16x16x32_bf16 v[122:125], v[182:185], v[190:193], 0
	v_mfma_f32_16x16x32_bf16 v[106:109], v[182:185], v[216:219], 0
	v_mfma_f32_16x16x32_bf16 v[114:117], v[158:161], v[216:219], 0
	v_mfma_f32_16x16x32_bf16 v[98:101], v[158:161], v[224:227], 0
	v_mfma_f32_16x16x32_bf16 v[90:93], v[182:185], v[224:227], 0
	v_mfma_f32_16x16x32_bf16 v[72:75], v[182:185], v[232:235], 0
	v_mfma_f32_16x16x32_bf16 v[82:85], v[158:161], v[232:235], 0
	v_mfma_f32_16x16x32_bf16 v[130:133], v[178:181], v[212:215], v[130:133]
	v_mfma_f32_16x16x32_bf16 v[122:125], v[186:189], v[212:215], v[122:125]
	v_mfma_f32_16x16x32_bf16 v[106:109], v[186:189], v[220:223], v[106:109]
	v_mfma_f32_16x16x32_bf16 v[114:117], v[178:181], v[220:223], v[114:117]
	v_mfma_f32_16x16x32_bf16 v[98:101], v[178:181], v[228:231], v[98:101]
	v_mfma_f32_16x16x32_bf16 v[90:93], v[186:189], v[228:231], v[90:93]
	v_mfma_f32_16x16x32_bf16 v[72:75], v[186:189], v[236:239], v[72:75]
	v_mfma_f32_16x16x32_bf16 v[82:85], v[178:181], v[236:239], v[82:85]
	s_setprio 0
	s_barrier
	s_add_i32 s76, s80, s13
	v_lshl_add_u64 v[194:195], s[88:89], 0, v[144:145]
	s_mov_b32 m0, s76
	s_nop 0
	global_load_lds_dwordx4 v[194:195], off
	s_add_i32 m0, s76, 0x2000
	s_add_u32 s76, s88, 0x40000
	v_lshl_add_u64 v[240:241], s[88:89], 0, v[148:149]
	s_addc_u32 s77, s89, 0
	s_add_i32 s80, s81, s13
	global_load_lds_dwordx4 v[240:241], off
	v_lshl_add_u64 v[242:243], s[76:77], 0, v[144:145]
	s_mov_b32 m0, s80
	v_lshl_add_u64 v[244:245], s[90:91], 0, v[146:147]
	global_load_lds_dwordx4 v[242:243], off
	v_lshl_add_u64 v[242:243], s[76:77], 0, v[148:149]
	s_add_i32 m0, s80, 0x2000
	s_nop 0
	global_load_lds_dwordx4 v[242:243], off
	v_lshl_add_u64 v[242:243], s[90:91], 0, v[142:143]
	s_mov_b32 m0, s15
	s_nop 0
	global_load_lds_dwordx4 v[242:243], off
	s_mov_b32 m0, s16
	s_nop 0
	global_load_lds_dwordx4 v[244:245], off
	ds_read_b128 v[190:193], v177 offset:16384
	ds_read_b128 v[212:215], v177 offset:17408
	ds_read_b128 v[216:219], v177 offset:18432
	ds_read_b128 v[220:223], v177 offset:19456
	ds_read_b128 v[224:227], v177 offset:20480
	ds_read_b128 v[228:231], v177 offset:21504
	ds_read_b128 v[232:235], v177 offset:22528
	ds_read_b128 v[236:239], v177 offset:23552
	s_waitcnt vmcnt(8)
	s_waitcnt lgkmcnt(0)
	s_barrier
; #define PG8_STAGE(bufoff, gbase, voff) do { _Pragma("unroll") for (int _i = 0; _i < 2; ++_i) \
;         __builtin_amdgcn_global_load_lds((const unsigned*)((const char*)(gbase) + (voff)[_i]), (PG8_LAS unsigned*)(lds + (bufoff) + ldsw + _i * 8192), 16, 0, 0); } while (0)
; #define PG8_LDA(dst, b, h) do { _Pragma("unroll") for (int m = 0; m < 4; ++m) _Pragma("unroll") for (int k = 0; k < 2; ++k) dst[m][k] = *(const PG8_LAS bf16x8*)(lds + PG8_SA(b, h) + aoff + m * 2048 + k * 1024); } while (0)
; #define PG8_LDB(dst, b, h) do { _Pragma("unroll") for (int n = 0; n < 2; ++n) _Pragma("unroll") for (int k = 0; k < 2; ++k) dst[n][k] = *(const PG8_LAS bf16x8*)(lds + PG8_SB(b, h) + boff + n * 2048 + k * 1024); } while (0)
; #define PG8_MMA(ai, bj, At, Bt) do { __builtin_amdgcn_s_setprio(1); _Pragma("unroll") for (int m = 0; m < 4; ++m) _Pragma("unroll") for (int n = 0; n < 2; ++n) _Pragma("unroll") for (int k = 0; k < 2; ++k) \
;         acc[ai][bj][m][n] = __builtin_amdgcn_mfma_f32_16x16x32_bf16(Bt[n][k], At[m][k], acc[ai][bj][m][n], 0, 0, 0); __builtin_amdgcn_s_setprio(0); } while (0)
; #define PG8_WAIT_V(n) asm volatile("s_waitcnt vmcnt(" #n ")" ::: "memory")
; #define PG8_WAIT_L(n) asm volatile("s_waitcnt lgkmcnt(" #n ")" ::: "memory")
; #define PG8_BAR __builtin_amdgcn_s_barrier()
; #define PG8_SCHED __builtin_amdgcn_sched_barrier(0)
; template <class Epi, class Sched, bool ALIGN_EPI = false, bool SP2 = false>
; __device__ __forceinline__ void gemm_phase(PG8_LAS unsigned char* lds, const Gemm g, const Sched& S, const Epi& E) {
;     ...
;             PG8_WAIT_V(8); PG8_WAIT_L(0); PG8_BAR; PG8_MMA(1, 0, At, B0); PG8_MMA(1, 1, At, B1); PG8_BAR; PG8_SCHED;
;             PG8_LDB(B0, 1, 0); PG8_LDB(B1, 1, 1); PG8_SCHED; PG8_LDA(At, 1, 0); PG8_STAGE(PG8_SA(0, 1), a2 + hstep, voffA);
;             PG8_WAIT_V(8); PG8_WAIT_L(0); PG8_BAR; PG8_MMA(0, 0, At, B0); PG8_MMA(0, 1, At, B1); PG8_BAR; PG8_SCHED;
	s_setprio 1
	s_waitcnt lgkmcnt(0)
	v_mfma_f32_16x16x32_bf16 v[68:71], v[48:51], v[190:193], 0
	v_mfma_f32_16x16x32_bf16 v[56:59], v[138:141], v[190:193], 0
	v_mfma_f32_16x16x32_bf16 v[36:39], v[138:141], v[216:219], 0
	v_mfma_f32_16x16x32_bf16 v[44:47], v[48:51], v[216:219], 0
	v_mfma_f32_16x16x32_bf16 v[28:31], v[48:51], v[224:227], 0
	v_mfma_f32_16x16x32_bf16 v[20:23], v[138:141], v[224:227], 0
	v_mfma_f32_16x16x32_bf16 v[4:7], v[138:141], v[232:235], 0
	v_mfma_f32_16x16x32_bf16 v[12:15], v[48:51], v[232:235], 0
	v_mfma_f32_16x16x32_bf16 v[68:71], v[60:63], v[212:215], v[68:71]
	v_mfma_f32_16x16x32_bf16 v[56:59], v[154:157], v[212:215], v[56:59]
	v_mfma_f32_16x16x32_bf16 v[36:39], v[154:157], v[220:223], v[36:39]
	v_mfma_f32_16x16x32_bf16 v[44:47], v[60:63], v[220:223], v[44:47]
	v_mfma_f32_16x16x32_bf16 v[28:31], v[60:63], v[228:231], v[28:31]
	v_mfma_f32_16x16x32_bf16 v[20:23], v[154:157], v[228:231], v[20:23]
	v_mfma_f32_16x16x32_bf16 v[4:7], v[154:157], v[236:239], v[4:7]
	v_mfma_f32_16x16x32_bf16 v[12:15], v[60:63], v[236:239], v[12:15]
	v_mfma_f32_16x16x32_bf16 v[52:55], v[182:185], v[190:193], 0
	v_mfma_f32_16x16x32_bf16 v[40:43], v[158:161], v[216:219], 0
	v_mfma_f32_16x16x32_bf16 v[32:35], v[182:185], v[216:219], 0
	v_mfma_f32_16x16x32_bf16 v[24:27], v[158:161], v[224:227], 0
	v_mfma_f32_16x16x32_bf16 v[16:19], v[182:185], v[224:227], 0
	v_mfma_f32_16x16x32_bf16 v[8:11], v[158:161], v[232:235], 0
	v_mfma_f32_16x16x32_bf16 v[0:3], v[182:185], v[232:235], 0
	v_mfma_f32_16x16x32_bf16 v[48:51], v[158:161], v[190:193], 0
	v_mfma_f32_16x16x32_bf16 v[52:55], v[186:189], v[212:215], v[52:55]
	v_mfma_f32_16x16x32_bf16 v[40:43], v[178:181], v[220:223], v[40:43]
	v_mfma_f32_16x16x32_bf16 v[32:35], v[186:189], v[220:223], v[32:35]
	v_mfma_f32_16x16x32_bf16 v[24:27], v[178:181], v[228:231], v[24:27]
	v_mfma_f32_16x16x32_bf16 v[16:19], v[186:189], v[228:231], v[16:19]
	v_mfma_f32_16x16x32_bf16 v[8:11], v[178:181], v[236:239], v[8:11]
	v_mfma_f32_16x16x32_bf16 v[0:3], v[186:189], v[236:239], v[0:3]
	v_mfma_f32_16x16x32_bf16 v[48:51], v[178:181], v[212:215], v[48:51]
	s_setprio 0
	s_barrier
	s_add_i32 s80, 0, 0x18000
	s_add_i32 s81, 0, 0x1c000
	v_add_u32_e32 v154, s80, v176
	v_add_u32_e32 v186, s81, v176
	s_add_u32 s76, s90, 0x40000
	s_addc_u32 s77, s91, 0
	s_mov_b32 m0, s17
	v_lshl_add_u64 v[246:247], s[76:77], 0, v[142:143]
	global_load_lds_dwordx4 v[246:247], off
	v_lshl_add_u64 v[246:247], s[76:77], 0, v[146:147]
	s_mov_b32 m0, s18
	s_nop 0
	global_load_lds_dwordx4 v[246:247], off
	ds_read_b128 v[60:63], v154
	ds_read_b128 v[64:67], v154 offset:1024
	ds_read_b128 v[138:141], v154 offset:2048
	ds_read_b128 v[154:157], v154 offset:3072
	ds_read_b128 v[158:161], v186
	ds_read_b128 v[178:181], v186 offset:1024
	ds_read_b128 v[182:185], v186 offset:2048
	ds_read_b128 v[186:189], v186 offset:3072
	ds_read_b128 v[190:193], v177 offset:32768
	ds_read_b128 v[212:215], v177 offset:33792
	ds_read_b128 v[216:219], v177 offset:34816
	ds_read_b128 v[220:223], v177 offset:35840
	ds_read_b128 v[224:227], v177 offset:36864
	ds_read_b128 v[228:231], v177 offset:37888
	ds_read_b128 v[232:235], v177 offset:38912
	ds_read_b128 v[236:239], v177 offset:39936
	s_waitcnt vmcnt(8)
	s_waitcnt lgkmcnt(0)
	s_barrier
	s_setprio 1
	s_waitcnt lgkmcnt(0)
	v_mfma_f32_16x16x32_bf16 v[134:137], v[60:63], v[190:193], v[134:137]
	v_mfma_f32_16x16x32_bf16 v[126:129], v[138:141], v[190:193], v[126:129]
	v_mfma_f32_16x16x32_bf16 v[110:113], v[138:141], v[216:219], v[110:113]
	v_mfma_f32_16x16x32_bf16 v[118:121], v[60:63], v[216:219], v[118:121]
	v_mfma_f32_16x16x32_bf16 v[102:105], v[60:63], v[224:227], v[102:105]
	v_mfma_f32_16x16x32_bf16 v[94:97], v[138:141], v[224:227], v[94:97]
	v_mfma_f32_16x16x32_bf16 v[76:79], v[138:141], v[232:235], v[76:79]
	v_mfma_f32_16x16x32_bf16 v[86:89], v[60:63], v[232:235], v[86:89]
	v_mfma_f32_16x16x32_bf16 v[134:137], v[64:67], v[212:215], v[134:137]
	v_mfma_f32_16x16x32_bf16 v[126:129], v[154:157], v[212:215], v[126:129]
	v_mfma_f32_16x16x32_bf16 v[110:113], v[154:157], v[220:223], v[110:113]
	v_mfma_f32_16x16x32_bf16 v[118:121], v[64:67], v[220:223], v[118:121]
	v_mfma_f32_16x16x32_bf16 v[102:105], v[64:67], v[228:231], v[102:105]
	v_mfma_f32_16x16x32_bf16 v[94:97], v[154:157], v[228:231], v[94:97]
	v_mfma_f32_16x16x32_bf16 v[76:79], v[154:157], v[236:239], v[76:79]
	v_mfma_f32_16x16x32_bf16 v[86:89], v[64:67], v[236:239], v[86:89]
	v_mfma_f32_16x16x32_bf16 v[130:133], v[158:161], v[190:193], v[130:133]
	v_mfma_f32_16x16x32_bf16 v[122:125], v[182:185], v[190:193], v[122:125]
	v_mfma_f32_16x16x32_bf16 v[106:109], v[182:185], v[216:219], v[106:109]
	v_mfma_f32_16x16x32_bf16 v[114:117], v[158:161], v[216:219], v[114:117]
	v_mfma_f32_16x16x32_bf16 v[98:101], v[158:161], v[224:227], v[98:101]
	v_mfma_f32_16x16x32_bf16 v[90:93], v[182:185], v[224:227], v[90:93]
	v_mfma_f32_16x16x32_bf16 v[72:75], v[182:185], v[232:235], v[72:75]
	v_mfma_f32_16x16x32_bf16 v[82:85], v[158:161], v[232:235], v[82:85]
	v_mfma_f32_16x16x32_bf16 v[130:133], v[178:181], v[212:215], v[130:133]
	v_mfma_f32_16x16x32_bf16 v[122:125], v[186:189], v[212:215], v[122:125]
	v_mfma_f32_16x16x32_bf16 v[106:109], v[186:189], v[220:223], v[106:109]
	v_mfma_f32_16x16x32_bf16 v[114:117], v[178:181], v[220:223], v[114:117]
	v_mfma_f32_16x16x32_bf16 v[98:101], v[178:181], v[228:231], v[98:101]
	v_mfma_f32_16x16x32_bf16 v[90:93], v[186:189], v[228:231], v[90:93]
	v_mfma_f32_16x16x32_bf16 v[72:75], v[186:189], v[236:239], v[72:75]
	v_mfma_f32_16x16x32_bf16 v[82:85], v[178:181], v[236:239], v[82:85]
	s_setprio 0
	s_barrier
; #define PG8_STAGE(bufoff, gbase, voff) do { _Pragma("unroll") for (int _i = 0; _i < 2; ++_i) \
;         __builtin_amdgcn_global_load_lds((const unsigned*)((const char*)(gbase) + (voff)[_i]), (PG8_LAS unsigned*)(lds + (bufoff) + ldsw + _i * 8192), 16, 0, 0); } while (0)
; #define PG8_LDA(dst, b, h) do { _Pragma("unroll") for (int m = 0; m < 4; ++m) _Pragma("unroll") for (int k = 0; k < 2; ++k) dst[m][k] = *(const PG8_LAS bf16x8*)(lds + PG8_SA(b, h) + aoff + m * 2048 + k * 1024); } while (0)
; #define PG8_LDB(dst, b, h) do { _Pragma("unroll") for (int n = 0; n < 2; ++n) _Pragma("unroll") for (int k = 0; k < 2; ++k) dst[n][k] = *(const PG8_LAS bf16x8*)(lds + PG8_SB(b, h) + boff + n * 2048 + k * 1024); } while (0)
; #define PG8_BAR __builtin_amdgcn_s_barrier()
; template <class Epi, class Sched, bool ALIGN_EPI = false, bool SP2 = false>
; __device__ __forceinline__ void gemm_phase(PG8_LAS unsigned char* lds, const Gemm g, const Sched& S, const Epi& E) {
;     ...
;             const bool last = (t == nt - 2);
;             const char* a1 = cA + (size_t)(t + 1) * kstep;
;             const char* a2 = last ? nA : cA + (size_t)(t + 2) * kstep; const char* b2 = last ? nB : cB + (size_t)(t + 2) * kstep;
;             const char* a3 = a2 + kstep; const char* b3 = b2 + kstep;
;             if (last && has_next) S.a_ready(nxt);
;             if constexpr (SP2) {
;             PG8_LDB(B0, 0, 0); PG8_LDB(B1, 0, 1); PG8_SCHED; PG8_LDA(At, 0, 0); PG8_STAGE(PG8_SA(1, 1), a1 + hstep, voffA);
;             PG8_WAIT_V(8); PG8_WAIT_L(0); PG8_BAR; PG8_MMA(0, 0, At, B0); PG8_MMA(0, 1, At, B1); PG8_BAR; PG8_SCHED;
;             PG8_LDA(At, 0, 1); PG8_STAGE(PG8_SB(0, 0), b2, voffB); PG8_STAGE(PG8_SB(0, 1), b2 + hstep, voffB); PG8_STAGE(PG8_SA(0, 0), a2, voffA);
;             PG8_WAIT_V(8); PG8_WAIT_L(0); PG8_BAR; PG8_MMA(1, 0, At, B0); PG8_MMA(1, 1, At, B1); PG8_BAR; PG8_SCHED;
;             PG8_LDB(B0, 1, 0); PG8_LDB(B1, 1, 1); PG8_SCHED; PG8_LDA(At, 1, 0); PG8_STAGE(PG8_SA(0, 1), a2 + hstep, voffA);
;             PG8_WAIT_V(8); PG8_WAIT_L(0); PG8_BAR; PG8_MMA(0, 0, At, B0); PG8_MMA(0, 1, At, B1); PG8_BAR; PG8_SCHED;
;             PG8_LDA(At, 1, 1); PG8_STAGE(PG8_SB(1, 0), b3, voffB); PG8_STAGE(PG8_SB(1, 1), b3 + hstep, voffB); PG8_STAGE(PG8_SA(1, 0), a3, voffA);
;             PG8_WAIT_V(8); PG8_WAIT_L(0); PG8_BAR; PG8_MMA(1, 0, At, B0); PG8_MMA(1, 1, At, B1); PG8_BAR; PG8_SCHED;
	s_add_i32 s76, s80, s13
	v_lshl_add_u64 v[194:195], v[194:195], 0, s[0:1]
	s_mov_b32 m0, s76
	s_nop 0
	global_load_lds_dwordx4 v[194:195], off
	s_add_i32 m0, s76, 0x2000
	s_add_u32 s76, s88, 0x40080
	v_lshl_add_u64 v[194:195], v[240:241], 0, s[0:1]
	s_addc_u32 s77, s89, 0
	s_add_i32 s80, s81, s13
	global_load_lds_dwordx4 v[194:195], off
	v_lshl_add_u64 v[194:195], s[76:77], 0, v[144:145]
	s_mov_b32 m0, s80
	s_nop 0
	global_load_lds_dwordx4 v[194:195], off
	v_lshl_add_u64 v[194:195], s[76:77], 0, v[148:149]
	s_add_i32 m0, s80, 0x2000
	s_nop 0
	global_load_lds_dwordx4 v[194:195], off
	v_lshl_add_u64 v[194:195], v[242:243], 0, s[0:1]
	s_mov_b32 m0, s21
	s_nop 0
	global_load_lds_dwordx4 v[194:195], off
	v_lshl_add_u64 v[194:195], v[244:245], 0, s[0:1]
	s_mov_b32 m0, s33
	s_nop 0
	global_load_lds_dwordx4 v[194:195], off
	ds_read_b128 v[190:193], v177 offset:49152
	ds_read_b128 v[212:215], v177 offset:50176
	ds_read_b128 v[216:219], v177 offset:51200
	ds_read_b128 v[220:223], v177 offset:52224
	ds_read_b128 v[224:227], v177 offset:53248
	ds_read_b128 v[228:231], v177 offset:54272
	ds_read_b128 v[232:235], v177 offset:55296
	ds_read_b128 v[236:239], v177 offset:56320
	s_waitcnt vmcnt(8)
	s_waitcnt lgkmcnt(0)
	s_barrier
	s_setprio 1
	s_waitcnt lgkmcnt(0)
	v_mfma_f32_16x16x32_bf16 v[68:71], v[60:63], v[190:193], v[68:71]
	v_mfma_f32_16x16x32_bf16 v[56:59], v[138:141], v[190:193], v[56:59]
	v_mfma_f32_16x16x32_bf16 v[36:39], v[138:141], v[216:219], v[36:39]
	v_mfma_f32_16x16x32_bf16 v[44:47], v[60:63], v[216:219], v[44:47]
	v_mfma_f32_16x16x32_bf16 v[28:31], v[60:63], v[224:227], v[28:31]
	v_mfma_f32_16x16x32_bf16 v[20:23], v[138:141], v[224:227], v[20:23]
	v_mfma_f32_16x16x32_bf16 v[4:7], v[138:141], v[232:235], v[4:7]
	v_mfma_f32_16x16x32_bf16 v[12:15], v[60:63], v[232:235], v[12:15]
	v_mfma_f32_16x16x32_bf16 v[68:71], v[64:67], v[212:215], v[68:71]
	v_mfma_f32_16x16x32_bf16 v[56:59], v[154:157], v[212:215], v[56:59]
	v_mfma_f32_16x16x32_bf16 v[36:39], v[154:157], v[220:223], v[36:39]
	v_mfma_f32_16x16x32_bf16 v[44:47], v[64:67], v[220:223], v[44:47]
	v_mfma_f32_16x16x32_bf16 v[28:31], v[64:67], v[228:231], v[28:31]
	v_mfma_f32_16x16x32_bf16 v[20:23], v[154:157], v[228:231], v[20:23]
	v_mfma_f32_16x16x32_bf16 v[4:7], v[154:157], v[236:239], v[4:7]
	v_mfma_f32_16x16x32_bf16 v[12:15], v[64:67], v[236:239], v[12:15]
	v_mfma_f32_16x16x32_bf16 v[48:51], v[158:161], v[190:193], v[48:51]
	v_mfma_f32_16x16x32_bf16 v[64:67], v[178:181], v[212:215], v[48:51]
	v_mfma_f32_16x16x32_bf16 v[48:51], v[182:185], v[190:193], v[52:55]
	v_mfma_f32_16x16x32_bf16 v[40:43], v[158:161], v[216:219], v[40:43]
	v_mfma_f32_16x16x32_bf16 v[32:35], v[182:185], v[216:219], v[32:35]
	v_mfma_f32_16x16x32_bf16 v[24:27], v[158:161], v[224:227], v[24:27]
	v_mfma_f32_16x16x32_bf16 v[16:19], v[182:185], v[224:227], v[16:19]
	v_mfma_f32_16x16x32_bf16 v[8:11], v[158:161], v[232:235], v[8:11]
	v_mfma_f32_16x16x32_bf16 v[0:3], v[182:185], v[232:235], v[0:3]
	v_mfma_f32_16x16x32_bf16 v[52:55], v[186:189], v[212:215], v[48:51]
	v_mfma_f32_16x16x32_bf16 v[40:43], v[178:181], v[220:223], v[40:43]
	v_mfma_f32_16x16x32_bf16 v[32:35], v[186:189], v[220:223], v[32:35]
	v_mfma_f32_16x16x32_bf16 v[24:27], v[178:181], v[228:231], v[24:27]
	v_mfma_f32_16x16x32_bf16 v[16:19], v[186:189], v[228:231], v[16:19]
	v_mfma_f32_16x16x32_bf16 v[0:3], v[186:189], v[236:239], v[0:3]
	v_mfma_f32_16x16x32_bf16 v[8:11], v[178:181], v[236:239], v[8:11]
	s_setprio 0
	s_barrier
	s_add_i32 s75, s75, 2
	s_add_u32 s86, s86, 0x100
	s_addc_u32 s87, s87, 0
	s_add_u32 s69, s69, 0x100
	s_addc_u32 s71, s71, 0
	s_cmp_gt_u32 s75, 13
	s_cbranch_scc1 .Lpeel_done_2
.LBB0_236:
	s_add_u32 s76, s86, 0xfffc0080
	s_addc_u32 s77, s87, -1
	s_add_i32 s80, 0, 0x10000
	s_cmp_eq_u32 s75, 12
	s_cselect_b32 s91, s66, s77
	s_cselect_b32 s90, s67, s76
	s_cselect_b32 s89, s39, s71
	s_cselect_b32 s88, s68, s69
	s_add_i32 s81, 0, 0x14000
	v_add_u32_e32 v154, s80, v176
	v_add_u32_e32 v186, s81, v176
	v_lshl_add_u64 v[194:195], s[86:87], 0, v[150:151]
	s_add_i32 m0, s15, 0xc000
	s_nop 0
	global_load_lds_dwordx4 v[194:195], off
	v_lshl_add_u64 v[194:195], s[86:87], 0, v[152:153]
	s_add_i32 m0, s15, 0xe000
	s_nop 0
	global_load_lds_dwordx4 v[194:195], off
	ds_read_b128 v[48:51], v154
	ds_read_b128 v[60:63], v154 offset:1024
	ds_read_b128 v[138:141], v154 offset:2048
	ds_read_b128 v[154:157], v154 offset:3072
	ds_read_b128 v[158:161], v186
	ds_read_b128 v[178:181], v186 offset:1024
	ds_read_b128 v[182:185], v186 offset:2048
	ds_read_b128 v[186:189], v186 offset:3072
	ds_read_b128 v[190:193], v177
	ds_read_b128 v[212:215], v177 offset:1024
	ds_read_b128 v[216:219], v177 offset:2048
	ds_read_b128 v[220:223], v177 offset:3072
	ds_read_b128 v[224:227], v177 offset:4096
	ds_read_b128 v[228:231], v177 offset:5120
	ds_read_b128 v[232:235], v177 offset:6144
	ds_read_b128 v[236:239], v177 offset:7168
	s_waitcnt vmcnt(8)
	s_waitcnt lgkmcnt(0)
	s_barrier
; #define PG8_STAGE(bufoff, gbase, voff) do { _Pragma("unroll") for (int _i = 0; _i < 2; ++_i) \
;         __builtin_amdgcn_global_load_lds((const unsigned*)((const char*)(gbase) + (voff)[_i]), (PG8_LAS unsigned*)(lds + (bufoff) + ldsw + _i * 8192), 16, 0, 0); } while (0)
; #define PG8_LDA(dst, b, h) do { _Pragma("unroll") for (int m = 0; m < 4; ++m) _Pragma("unroll") for (int k = 0; k < 2; ++k) dst[m][k] = *(const PG8_LAS bf16x8*)(lds + PG8_SA(b, h) + aoff + m * 2048 + k * 1024); } while (0)
; #define PG8_MMA(ai, bj, At, Bt) do { __builtin_amdgcn_s_setprio(1); _Pragma("unroll") for (int m = 0; m < 4; ++m) _Pragma("unroll") for (int n = 0; n < 2; ++n) _Pragma("unroll") for (int k = 0; k < 2; ++k) \
;         acc[ai][bj][m][n] = __builtin_amdgcn_mfma_f32_16x16x32_bf16(Bt[n][k], At[m][k], acc[ai][bj][m][n], 0, 0, 0); __builtin_amdgcn_s_setprio(0); } while (0)
; #define PG8_WAIT_V(n) asm volatile("s_waitcnt vmcnt(" #n ")" ::: "memory")
; #define PG8_WAIT_L(n) asm volatile("s_waitcnt lgkmcnt(" #n ")" ::: "memory")
; #define PG8_BAR __builtin_amdgcn_s_barrier()
; #define PG8_SCHED __builtin_amdgcn_sched_barrier(0)
; template <class Epi, class Sched, bool ALIGN_EPI = false, bool SP2 = false>
; __device__ __forceinline__ void gemm_phase(PG8_LAS unsigned char* lds, const Gemm g, const Sched& S, const Epi& E) {
;     ...
;             PG8_WAIT_V(8); PG8_WAIT_L(0); PG8_BAR; PG8_MMA(0, 0, At, B0); PG8_MMA(0, 1, At, B1); PG8_BAR; PG8_SCHED;
;             PG8_LDA(At, 0, 1); PG8_STAGE(PG8_SB(0, 0), b2, voffB); PG8_STAGE(PG8_SB(0, 1), b2 + hstep, voffB); PG8_STAGE(PG8_SA(0, 0), a2, voffA);
;             PG8_WAIT_V(8); PG8_WAIT_L(0); PG8_BAR; PG8_MMA(1, 0, At, B0); PG8_MMA(1, 1, At, B1); PG8_BAR; PG8_SCHED;
	s_setprio 1
	s_waitcnt lgkmcnt(0)
	v_mfma_f32_16x16x32_bf16 v[134:137], v[48:51], v[190:193], v[134:137]
	v_mfma_f32_16x16x32_bf16 v[126:129], v[138:141], v[190:193], v[126:129]
	v_mfma_f32_16x16x32_bf16 v[110:113], v[138:141], v[216:219], v[110:113]
	v_mfma_f32_16x16x32_bf16 v[118:121], v[48:51], v[216:219], v[118:121]
	v_mfma_f32_16x16x32_bf16 v[102:105], v[48:51], v[224:227], v[102:105]
	v_mfma_f32_16x16x32_bf16 v[94:97], v[138:141], v[224:227], v[94:97]
	v_mfma_f32_16x16x32_bf16 v[76:79], v[138:141], v[232:235], v[76:79]
	v_mfma_f32_16x16x32_bf16 v[86:89], v[48:51], v[232:235], v[86:89]
	v_mfma_f32_16x16x32_bf16 v[134:137], v[60:63], v[212:215], v[134:137]
	v_mfma_f32_16x16x32_bf16 v[126:129], v[154:157], v[212:215], v[126:129]
	v_mfma_f32_16x16x32_bf16 v[110:113], v[154:157], v[220:223], v[110:113]
	v_mfma_f32_16x16x32_bf16 v[118:121], v[60:63], v[220:223], v[118:121]
	v_mfma_f32_16x16x32_bf16 v[102:105], v[60:63], v[228:231], v[102:105]
	v_mfma_f32_16x16x32_bf16 v[94:97], v[154:157], v[228:231], v[94:97]
	v_mfma_f32_16x16x32_bf16 v[76:79], v[154:157], v[236:239], v[76:79]
	v_mfma_f32_16x16x32_bf16 v[86:89], v[60:63], v[236:239], v[86:89]
	v_mfma_f32_16x16x32_bf16 v[130:133], v[158:161], v[190:193], v[130:133]
	v_mfma_f32_16x16x32_bf16 v[122:125], v[182:185], v[190:193], v[122:125]
	v_mfma_f32_16x16x32_bf16 v[106:109], v[182:185], v[216:219], v[106:109]
	v_mfma_f32_16x16x32_bf16 v[114:117], v[158:161], v[216:219], v[114:117]
	v_mfma_f32_16x16x32_bf16 v[98:101], v[158:161], v[224:227], v[98:101]
	v_mfma_f32_16x16x32_bf16 v[90:93], v[182:185], v[224:227], v[90:93]
	v_mfma_f32_16x16x32_bf16 v[72:75], v[182:185], v[232:235], v[72:75]
	v_mfma_f32_16x16x32_bf16 v[82:85], v[158:161], v[232:235], v[82:85]
	v_mfma_f32_16x16x32_bf16 v[130:133], v[178:181], v[212:215], v[130:133]
	v_mfma_f32_16x16x32_bf16 v[122:125], v[186:189], v[212:215], v[122:125]
	v_mfma_f32_16x16x32_bf16 v[106:109], v[186:189], v[220:223], v[106:109]
	v_mfma_f32_16x16x32_bf16 v[114:117], v[178:181], v[220:223], v[114:117]
	v_mfma_f32_16x16x32_bf16 v[98:101], v[178:181], v[228:231], v[98:101]
	v_mfma_f32_16x16x32_bf16 v[90:93], v[186:189], v[228:231], v[90:93]
	v_mfma_f32_16x16x32_bf16 v[72:75], v[186:189], v[236:239], v[72:75]
	v_mfma_f32_16x16x32_bf16 v[82:85], v[178:181], v[236:239], v[82:85]
	s_setprio 0
	s_barrier
	s_add_i32 s76, s80, s13
	v_lshl_add_u64 v[194:195], s[88:89], 0, v[144:145]
	s_mov_b32 m0, s76
	s_nop 0
	global_load_lds_dwordx4 v[194:195], off
	s_add_i32 m0, s76, 0x2000
	s_add_u32 s76, s88, 0x40000
	v_lshl_add_u64 v[240:241], s[88:89], 0, v[148:149]
	s_addc_u32 s77, s89, 0
	s_add_i32 s80, s81, s13
	global_load_lds_dwordx4 v[240:241], off
	v_lshl_add_u64 v[242:243], s[76:77], 0, v[144:145]
	s_mov_b32 m0, s80
	v_lshl_add_u64 v[244:245], s[90:91], 0, v[146:147]
	global_load_lds_dwordx4 v[242:243], off
	v_lshl_add_u64 v[242:243], s[76:77], 0, v[148:149]
	s_add_i32 m0, s80, 0x2000
	s_nop 0
	global_load_lds_dwordx4 v[242:243], off
	v_lshl_add_u64 v[242:243], s[90:91], 0, v[142:143]
	s_mov_b32 m0, s15
	s_nop 0
	global_load_lds_dwordx4 v[242:243], off
	s_mov_b32 m0, s16
	s_nop 0
	global_load_lds_dwordx4 v[244:245], off
	ds_read_b128 v[190:193], v177 offset:16384
	ds_read_b128 v[212:215], v177 offset:17408
	ds_read_b128 v[216:219], v177 offset:18432
	ds_read_b128 v[220:223], v177 offset:19456
	ds_read_b128 v[224:227], v177 offset:20480
	ds_read_b128 v[228:231], v177 offset:21504
	ds_read_b128 v[232:235], v177 offset:22528
	ds_read_b128 v[236:239], v177 offset:23552
	s_waitcnt vmcnt(8)
	s_waitcnt lgkmcnt(0)
	s_barrier
	s_setprio 1
	s_waitcnt lgkmcnt(0)
	v_mfma_f32_16x16x32_bf16 v[68:71], v[48:51], v[190:193], v[68:71]
	v_mfma_f32_16x16x32_bf16 v[56:59], v[138:141], v[190:193], v[56:59]
	v_mfma_f32_16x16x32_bf16 v[36:39], v[138:141], v[216:219], v[36:39]
	v_mfma_f32_16x16x32_bf16 v[44:47], v[48:51], v[216:219], v[44:47]
	v_mfma_f32_16x16x32_bf16 v[28:31], v[48:51], v[224:227], v[28:31]
	v_mfma_f32_16x16x32_bf16 v[20:23], v[138:141], v[224:227], v[20:23]
	v_mfma_f32_16x16x32_bf16 v[4:7], v[138:141], v[232:235], v[4:7]
	v_mfma_f32_16x16x32_bf16 v[12:15], v[48:51], v[232:235], v[12:15]
	v_mfma_f32_16x16x32_bf16 v[68:71], v[60:63], v[212:215], v[68:71]
	v_mfma_f32_16x16x32_bf16 v[56:59], v[154:157], v[212:215], v[56:59]
	v_mfma_f32_16x16x32_bf16 v[36:39], v[154:157], v[220:223], v[36:39]
	v_mfma_f32_16x16x32_bf16 v[44:47], v[60:63], v[220:223], v[44:47]
	v_mfma_f32_16x16x32_bf16 v[28:31], v[60:63], v[228:231], v[28:31]
	v_mfma_f32_16x16x32_bf16 v[20:23], v[154:157], v[228:231], v[20:23]
	v_mfma_f32_16x16x32_bf16 v[4:7], v[154:157], v[236:239], v[4:7]
	v_mfma_f32_16x16x32_bf16 v[12:15], v[60:63], v[236:239], v[12:15]
	v_mfma_f32_16x16x32_bf16 v[52:55], v[182:185], v[190:193], v[52:55]
	v_mfma_f32_16x16x32_bf16 v[40:43], v[158:161], v[216:219], v[40:43]
	v_mfma_f32_16x16x32_bf16 v[32:35], v[182:185], v[216:219], v[32:35]
	v_mfma_f32_16x16x32_bf16 v[24:27], v[158:161], v[224:227], v[24:27]
	v_mfma_f32_16x16x32_bf16 v[16:19], v[182:185], v[224:227], v[16:19]
	v_mfma_f32_16x16x32_bf16 v[8:11], v[158:161], v[232:235], v[8:11]
	v_mfma_f32_16x16x32_bf16 v[0:3], v[182:185], v[232:235], v[0:3]
	v_mfma_f32_16x16x32_bf16 v[48:51], v[158:161], v[190:193], v[64:67]
	v_mfma_f32_16x16x32_bf16 v[52:55], v[186:189], v[212:215], v[52:55]
	v_mfma_f32_16x16x32_bf16 v[40:43], v[178:181], v[220:223], v[40:43]
	v_mfma_f32_16x16x32_bf16 v[32:35], v[186:189], v[220:223], v[32:35]
	v_mfma_f32_16x16x32_bf16 v[24:27], v[178:181], v[228:231], v[24:27]
	v_mfma_f32_16x16x32_bf16 v[16:19], v[186:189], v[228:231], v[16:19]
	v_mfma_f32_16x16x32_bf16 v[8:11], v[178:181], v[236:239], v[8:11]
	v_mfma_f32_16x16x32_bf16 v[0:3], v[186:189], v[236:239], v[0:3]
	v_mfma_f32_16x16x32_bf16 v[48:51], v[178:181], v[212:215], v[48:51]
	s_setprio 0
	s_barrier
; #define PG8_STAGE(bufoff, gbase, voff) do { _Pragma("unroll") for (int _i = 0; _i < 2; ++_i) \
;         __builtin_amdgcn_global_load_lds((const unsigned*)((const char*)(gbase) + (voff)[_i]), (PG8_LAS unsigned*)(lds + (bufoff) + ldsw + _i * 8192), 16, 0, 0); } while (0)
; #define PG8_LDA(dst, b, h) do { _Pragma("unroll") for (int m = 0; m < 4; ++m) _Pragma("unroll") for (int k = 0; k < 2; ++k) dst[m][k] = *(const PG8_LAS bf16x8*)(lds + PG8_SA(b, h) + aoff + m * 2048 + k * 1024); } while (0)
; #define PG8_LDB(dst, b, h) do { _Pragma("unroll") for (int n = 0; n < 2; ++n) _Pragma("unroll") for (int k = 0; k < 2; ++k) dst[n][k] = *(const PG8_LAS bf16x8*)(lds + PG8_SB(b, h) + boff + n * 2048 + k * 1024); } while (0)
; #define PG8_MMA(ai, bj, At, Bt) do { __builtin_amdgcn_s_setprio(1); _Pragma("unroll") for (int m = 0; m < 4; ++m) _Pragma("unroll") for (int n = 0; n < 2; ++n) _Pragma("unroll") for (int k = 0; k < 2; ++k) \
;         acc[ai][bj][m][n] = __builtin_amdgcn_mfma_f32_16x16x32_bf16(Bt[n][k], At[m][k], acc[ai][bj][m][n], 0, 0, 0); __builtin_amdgcn_s_setprio(0); } while (0)
; #define PG8_WAIT_V(n) asm volatile("s_waitcnt vmcnt(" #n ")" ::: "memory")
; #define PG8_WAIT_L(n) asm volatile("s_waitcnt lgkmcnt(" #n ")" ::: "memory")
; #define PG8_BAR __builtin_amdgcn_s_barrier()
; #define PG8_SCHED __builtin_amdgcn_sched_barrier(0)
; template <class Epi, class Sched, bool ALIGN_EPI = false, bool SP2 = false>
; __device__ __forceinline__ void gemm_phase(PG8_LAS unsigned char* lds, const Gemm g, const Sched& S, const Epi& E) {
;     ...
;             PG8_LDB(B0, 1, 0); PG8_LDB(B1, 1, 1); PG8_SCHED; PG8_LDA(At, 1, 0); PG8_STAGE(PG8_SA(0, 1), a2 + hstep, voffA);
;             PG8_WAIT_V(8); PG8_WAIT_L(0); PG8_BAR; PG8_MMA(0, 0, At, B0); PG8_MMA(0, 1, At, B1); PG8_BAR; PG8_SCHED;
	s_add_i32 s80, 0, 0x18000
	s_add_i32 s81, 0, 0x1c000
	v_add_u32_e32 v154, s80, v176
	v_add_u32_e32 v186, s81, v176
	s_add_u32 s76, s90, 0x40000
	s_addc_u32 s77, s91, 0
	s_mov_b32 m0, s17
	v_lshl_add_u64 v[246:247], s[76:77], 0, v[142:143]
	global_load_lds_dwordx4 v[246:247], off
	v_lshl_add_u64 v[246:247], s[76:77], 0, v[146:147]
	s_mov_b32 m0, s18
	s_nop 0
	global_load_lds_dwordx4 v[246:247], off
	ds_read_b128 v[60:63], v154
	ds_read_b128 v[64:67], v154 offset:1024
	ds_read_b128 v[138:141], v154 offset:2048
	ds_read_b128 v[154:157], v154 offset:3072
	ds_read_b128 v[158:161], v186
	ds_read_b128 v[178:181], v186 offset:1024
	ds_read_b128 v[182:185], v186 offset:2048
	ds_read_b128 v[186:189], v186 offset:3072
	ds_read_b128 v[190:193], v177 offset:32768
	ds_read_b128 v[212:215], v177 offset:33792
	ds_read_b128 v[216:219], v177 offset:34816
	ds_read_b128 v[220:223], v177 offset:35840
	ds_read_b128 v[224:227], v177 offset:36864
	ds_read_b128 v[228:231], v177 offset:37888
	ds_read_b128 v[232:235], v177 offset:38912
	ds_read_b128 v[236:239], v177 offset:39936
	s_waitcnt vmcnt(8)
	s_waitcnt lgkmcnt(0)
	s_barrier
	s_setprio 1
	s_waitcnt lgkmcnt(0)
	v_mfma_f32_16x16x32_bf16 v[134:137], v[60:63], v[190:193], v[134:137]
	v_mfma_f32_16x16x32_bf16 v[126:129], v[138:141], v[190:193], v[126:129]
	v_mfma_f32_16x16x32_bf16 v[110:113], v[138:141], v[216:219], v[110:113]
	v_mfma_f32_16x16x32_bf16 v[118:121], v[60:63], v[216:219], v[118:121]
	v_mfma_f32_16x16x32_bf16 v[102:105], v[60:63], v[224:227], v[102:105]
	v_mfma_f32_16x16x32_bf16 v[94:97], v[138:141], v[224:227], v[94:97]
	v_mfma_f32_16x16x32_bf16 v[76:79], v[138:141], v[232:235], v[76:79]
	v_mfma_f32_16x16x32_bf16 v[86:89], v[60:63], v[232:235], v[86:89]
	v_mfma_f32_16x16x32_bf16 v[134:137], v[64:67], v[212:215], v[134:137]
	v_mfma_f32_16x16x32_bf16 v[126:129], v[154:157], v[212:215], v[126:129]
	v_mfma_f32_16x16x32_bf16 v[110:113], v[154:157], v[220:223], v[110:113]
	v_mfma_f32_16x16x32_bf16 v[118:121], v[64:67], v[220:223], v[118:121]
	v_mfma_f32_16x16x32_bf16 v[102:105], v[64:67], v[228:231], v[102:105]
	v_mfma_f32_16x16x32_bf16 v[94:97], v[154:157], v[228:231], v[94:97]
	v_mfma_f32_16x16x32_bf16 v[76:79], v[154:157], v[236:239], v[76:79]
	v_mfma_f32_16x16x32_bf16 v[86:89], v[64:67], v[236:239], v[86:89]
	v_mfma_f32_16x16x32_bf16 v[130:133], v[158:161], v[190:193], v[130:133]
	v_mfma_f32_16x16x32_bf16 v[122:125], v[182:185], v[190:193], v[122:125]
	v_mfma_f32_16x16x32_bf16 v[106:109], v[182:185], v[216:219], v[106:109]
	v_mfma_f32_16x16x32_bf16 v[114:117], v[158:161], v[216:219], v[114:117]
	v_mfma_f32_16x16x32_bf16 v[98:101], v[158:161], v[224:227], v[98:101]
	v_mfma_f32_16x16x32_bf16 v[90:93], v[182:185], v[224:227], v[90:93]
	v_mfma_f32_16x16x32_bf16 v[72:75], v[182:185], v[232:235], v[72:75]
	v_mfma_f32_16x16x32_bf16 v[82:85], v[158:161], v[232:235], v[82:85]
	v_mfma_f32_16x16x32_bf16 v[130:133], v[178:181], v[212:215], v[130:133]
	v_mfma_f32_16x16x32_bf16 v[122:125], v[186:189], v[212:215], v[122:125]
	v_mfma_f32_16x16x32_bf16 v[106:109], v[186:189], v[220:223], v[106:109]
	v_mfma_f32_16x16x32_bf16 v[114:117], v[178:181], v[220:223], v[114:117]
	v_mfma_f32_16x16x32_bf16 v[98:101], v[178:181], v[228:231], v[98:101]
	v_mfma_f32_16x16x32_bf16 v[90:93], v[186:189], v[228:231], v[90:93]
	v_mfma_f32_16x16x32_bf16 v[72:75], v[186:189], v[236:239], v[72:75]
	v_mfma_f32_16x16x32_bf16 v[82:85], v[178:181], v[236:239], v[82:85]
	s_setprio 0
	s_barrier
; #define PG8_STAGE(bufoff, gbase, voff) do { _Pragma("unroll") for (int _i = 0; _i < 2; ++_i) \
;         __builtin_amdgcn_global_load_lds((const unsigned*)((const char*)(gbase) + (voff)[_i]), (PG8_LAS unsigned*)(lds + (bufoff) + ldsw + _i * 8192), 16, 0, 0); } while (0)
; #define PG8_LDA(dst, b, h) do { _Pragma("unroll") for (int m = 0; m < 4; ++m) _Pragma("unroll") for (int k = 0; k < 2; ++k) dst[m][k] = *(const PG8_LAS bf16x8*)(lds + PG8_SA(b, h) + aoff + m * 2048 + k * 1024); } while (0)
; #define PG8_MMA(ai, bj, At, Bt) do { __builtin_amdgcn_s_setprio(1); _Pragma("unroll") for (int m = 0; m < 4; ++m) _Pragma("unroll") for (int n = 0; n < 2; ++n) _Pragma("unroll") for (int k = 0; k < 2; ++k) \
;         acc[ai][bj][m][n] = __builtin_amdgcn_mfma_f32_16x16x32_bf16(Bt[n][k], At[m][k], acc[ai][bj][m][n], 0, 0, 0); __builtin_amdgcn_s_setprio(0); } while (0)
; #define PG8_WAIT_V(n) asm volatile("s_waitcnt vmcnt(" #n ")" ::: "memory")
; #define PG8_WAIT_L(n) asm volatile("s_waitcnt lgkmcnt(" #n ")" ::: "memory")
; #define PG8_BAR __builtin_amdgcn_s_barrier()
; #define PG8_SCHED __builtin_amdgcn_sched_barrier(0)
; template <class Epi, class Sched, bool ALIGN_EPI = false, bool SP2 = false>
; __device__ __forceinline__ void gemm_phase(PG8_LAS unsigned char* lds, const Gemm g, const Sched& S, const Epi& E) {
;     ...
;             PG8_LDA(At, 1, 1); PG8_STAGE(PG8_SB(1, 0), b3, voffB); PG8_STAGE(PG8_SB(1, 1), b3 + hstep, voffB); PG8_STAGE(PG8_SA(1, 0), a3, voffA);
;             PG8_WAIT_V(8); PG8_WAIT_L(0); PG8_BAR; PG8_MMA(1, 0, At, B0); PG8_MMA(1, 1, At, B1); PG8_BAR; PG8_SCHED;
	s_add_i32 s76, s80, s13
	v_lshl_add_u64 v[194:195], v[194:195], 0, s[0:1]
	s_mov_b32 m0, s76
	s_nop 0
	global_load_lds_dwordx4 v[194:195], off
	s_add_i32 m0, s76, 0x2000
	s_add_u32 s76, s88, 0x40080
	v_lshl_add_u64 v[194:195], v[240:241], 0, s[0:1]
	s_addc_u32 s77, s89, 0
	s_add_i32 s80, s81, s13
	global_load_lds_dwordx4 v[194:195], off
	v_lshl_add_u64 v[194:195], s[76:77], 0, v[144:145]
	s_mov_b32 m0, s80
	s_nop 0
	global_load_lds_dwordx4 v[194:195], off
	v_lshl_add_u64 v[194:195], s[76:77], 0, v[148:149]
	s_add_i32 m0, s80, 0x2000
	s_nop 0
	global_load_lds_dwordx4 v[194:195], off
	v_lshl_add_u64 v[194:195], v[242:243], 0, s[0:1]
	s_mov_b32 m0, s21
	s_nop 0
	global_load_lds_dwordx4 v[194:195], off
	v_lshl_add_u64 v[194:195], v[244:245], 0, s[0:1]
	s_mov_b32 m0, s33
	s_nop 0
	global_load_lds_dwordx4 v[194:195], off
	ds_read_b128 v[190:193], v177 offset:49152
	ds_read_b128 v[212:215], v177 offset:50176
	ds_read_b128 v[216:219], v177 offset:51200
	ds_read_b128 v[220:223], v177 offset:52224
	ds_read_b128 v[224:227], v177 offset:53248
	ds_read_b128 v[228:231], v177 offset:54272
	ds_read_b128 v[232:235], v177 offset:55296
	ds_read_b128 v[236:239], v177 offset:56320
	s_waitcnt vmcnt(8)
	s_waitcnt lgkmcnt(0)
	s_barrier
	s_setprio 1
	s_waitcnt lgkmcnt(0)
	v_mfma_f32_16x16x32_bf16 v[68:71], v[60:63], v[190:193], v[68:71]
	v_mfma_f32_16x16x32_bf16 v[56:59], v[138:141], v[190:193], v[56:59]
	v_mfma_f32_16x16x32_bf16 v[36:39], v[138:141], v[216:219], v[36:39]
	v_mfma_f32_16x16x32_bf16 v[44:47], v[60:63], v[216:219], v[44:47]
	v_mfma_f32_16x16x32_bf16 v[28:31], v[60:63], v[224:227], v[28:31]
	v_mfma_f32_16x16x32_bf16 v[20:23], v[138:141], v[224:227], v[20:23]
	v_mfma_f32_16x16x32_bf16 v[4:7], v[138:141], v[232:235], v[4:7]
	v_mfma_f32_16x16x32_bf16 v[12:15], v[60:63], v[232:235], v[12:15]
	v_mfma_f32_16x16x32_bf16 v[68:71], v[64:67], v[212:215], v[68:71]
	v_mfma_f32_16x16x32_bf16 v[56:59], v[154:157], v[212:215], v[56:59]
	v_mfma_f32_16x16x32_bf16 v[36:39], v[154:157], v[220:223], v[36:39]
	v_mfma_f32_16x16x32_bf16 v[44:47], v[64:67], v[220:223], v[44:47]
	v_mfma_f32_16x16x32_bf16 v[28:31], v[64:67], v[228:231], v[28:31]
	v_mfma_f32_16x16x32_bf16 v[20:23], v[154:157], v[228:231], v[20:23]
	v_mfma_f32_16x16x32_bf16 v[4:7], v[154:157], v[236:239], v[4:7]
	v_mfma_f32_16x16x32_bf16 v[12:15], v[64:67], v[236:239], v[12:15]
	v_mfma_f32_16x16x32_bf16 v[48:51], v[158:161], v[190:193], v[48:51]
	v_mfma_f32_16x16x32_bf16 v[64:67], v[178:181], v[212:215], v[48:51]
	v_mfma_f32_16x16x32_bf16 v[48:51], v[182:185], v[190:193], v[52:55]
	v_mfma_f32_16x16x32_bf16 v[40:43], v[158:161], v[216:219], v[40:43]
	v_mfma_f32_16x16x32_bf16 v[32:35], v[182:185], v[216:219], v[32:35]
	v_mfma_f32_16x16x32_bf16 v[24:27], v[158:161], v[224:227], v[24:27]
	v_mfma_f32_16x16x32_bf16 v[16:19], v[182:185], v[224:227], v[16:19]
	v_mfma_f32_16x16x32_bf16 v[8:11], v[158:161], v[232:235], v[8:11]
	v_mfma_f32_16x16x32_bf16 v[0:3], v[182:185], v[232:235], v[0:3]
	v_mfma_f32_16x16x32_bf16 v[52:55], v[186:189], v[212:215], v[48:51]
	v_mfma_f32_16x16x32_bf16 v[40:43], v[178:181], v[220:223], v[40:43]
	v_mfma_f32_16x16x32_bf16 v[32:35], v[186:189], v[220:223], v[32:35]
	v_mfma_f32_16x16x32_bf16 v[24:27], v[178:181], v[228:231], v[24:27]
	v_mfma_f32_16x16x32_bf16 v[16:19], v[186:189], v[228:231], v[16:19]
	v_mfma_f32_16x16x32_bf16 v[0:3], v[186:189], v[236:239], v[0:3]
	v_mfma_f32_16x16x32_bf16 v[8:11], v[178:181], v[236:239], v[8:11]
	s_setprio 0
	s_barrier
	s_add_i32 s75, s75, 2
	s_add_u32 s86, s86, 0x100
	s_addc_u32 s87, s87, 0
	s_add_u32 s69, s69, 0x100
	s_addc_u32 s71, s71, 0
	s_cmp_gt_u32 s75, 13
	s_cbranch_scc0 .LBB0_236

; #define PG8_STAGE(bufoff, gbase, voff) do { _Pragma("unroll") for (int _i = 0; _i < 2; ++_i) \
;         __builtin_amdgcn_global_load_lds((const unsigned*)((const char*)(gbase) + (voff)[_i]), (PG8_LAS unsigned*)(lds + (bufoff) + ldsw + _i * 8192), 16, 0, 0); } while (0)
; #define PG8_LDA(dst, b, h) do { _Pragma("unroll") for (int m = 0; m < 4; ++m) _Pragma("unroll") for (int k = 0; k < 2; ++k) dst[m][k] = *(const PG8_LAS bf16x8*)(lds + PG8_SA(b, h) + aoff + m * 2048 + k * 1024); } while (0)
; #define PG8_LDB(dst, b, h) do { _Pragma("unroll") for (int n = 0; n < 2; ++n) _Pragma("unroll") for (int k = 0; k < 2; ++k) dst[n][k] = *(const PG8_LAS bf16x8*)(lds + PG8_SB(b, h) + boff + n * 2048 + k * 1024); } while (0)
; #define PG8_WAIT_V(n) asm volatile("s_waitcnt vmcnt(" #n ")" ::: "memory")
; #define PG8_WAIT_L(n) asm volatile("s_waitcnt lgkmcnt(" #n ")" ::: "memory")
; #define PG8_BAR __builtin_amdgcn_s_barrier()
; template <class Epi, class Sched, bool ALIGN_EPI = false, bool SP2 = false>
; __device__ __forceinline__ void gemm_phase(PG8_LAS unsigned char* lds, const Gemm g, const Sched& S, const Epi& E) {
;     ...
;         const bool has_next = S.next(ui + 1, nxt);
;         const char* nA = has_next ? (const char*)g.A + (size_t)nxt.pm * tstep + (size_t)nxt.kt0 * kstep : cA; const char* nB = has_next ? (const char*)g.Bt + (size_t)nxt.pn * tstep + (size_t)nxt.kt0 * kstep : cB;
;         const int nt = cur.nt;
;         for (int t = 0; t < nt; t += 2) {
;             const bool last = (t == nt - 2);
;             const char* a1 = cA + (size_t)(t + 1) * kstep;
;             const char* a2 = last ? nA : cA + (size_t)(t + 2) * kstep; const char* b2 = last ? nB : cB + (size_t)(t + 2) * kstep;
;             const char* a3 = a2 + kstep; const char* b3 = b2 + kstep;
;             if (last && has_next) S.a_ready(nxt);
;             if constexpr (SP2) {
;             PG8_LDB(B0, 0, 0); PG8_LDB(B1, 0, 1); PG8_SCHED; PG8_LDA(At, 0, 0); PG8_STAGE(PG8_SA(1, 1), a1 + hstep, voffA);
;             PG8_WAIT_V(8); PG8_WAIT_L(0); PG8_BAR; PG8_MMA(0, 0, At, B0); PG8_MMA(0, 1, At, B1); PG8_BAR; PG8_SCHED;
;             PG8_LDA(At, 0, 1); PG8_STAGE(PG8_SB(0, 0), b2, voffB); PG8_STAGE(PG8_SB(0, 1), b2 + hstep, voffB); PG8_STAGE(PG8_SA(0, 0), a2, voffA);
;             PG8_WAIT_V(8); PG8_WAIT_L(0); PG8_BAR; PG8_MMA(1, 0, At, B0); PG8_MMA(1, 1, At, B1); PG8_BAR; PG8_SCHED;
.LBB0_315:
	s_ashr_i32 s31, s30, 31
	s_lshl_b64 s[8:9], s[30:31], 19
	s_add_u32 s74, s68, s8
	s_addc_u32 s75, s69, s9
	s_and_b64 s[8:9], s[36:37], exec
	s_cselect_b32 s3, s75, s41
	s_cselect_b32 s8, s74, s40
	s_ashr_i32 s87, s86, 31
	s_lshl_b64 s[10:11], s[86:87], 19
	v_readlane_b32 s9, v252, 31
	s_add_u32 s88, s9, s10
	v_readlane_b32 s9, v252, 32
	s_addc_u32 s89, s9, s11
	s_and_b64 s[10:11], s[36:37], exec
	s_cselect_b32 s9, s89, s43
	s_cselect_b32 s10, s88, s42
	s_add_u32 s40, s40, 0x40080
	s_addc_u32 s41, s41, 0
	s_add_u32 s11, s42, 0x100
	s_addc_u32 s12, s43, 0
	s_mov_b32 s13, -2
	s_waitcnt vmcnt(0)
	s_add_u32 s14, s40, 0xfffc0080
	s_addc_u32 s15, s41, -1
	s_add_i32 s16, 0, 0x10000
	s_cmp_eq_u32 s13, 12
	s_cselect_b32 s71, s3, s15
	s_cselect_b32 s70, s8, s14
	s_cselect_b32 s43, s9, s12
	s_cselect_b32 s42, s10, s11
	s_add_i32 s17, 0, 0x14000
	s_waitcnt lgkmcnt(0)
	v_add_u32_e32 v44, s16, v214
	v_add_u32_e32 v102, s17, v214
	ds_read_b128 v[32:35], v44
	ds_read_b128 v[36:39], v44 offset:1024
	ds_read_b128 v[40:43], v44 offset:2048
	ds_read_b128 v[44:47], v44 offset:3072
	ds_read_b128 v[90:93], v102
	ds_read_b128 v[94:97], v102 offset:1024
	ds_read_b128 v[98:101], v102 offset:2048
	ds_read_b128 v[102:105], v102 offset:3072
	v_lshl_add_u64 v[194:195], s[40:41], 0, v[178:179]
	s_add_i32 m0, s97, 0xc000
	ds_read_b128 v[182:185], v215
	ds_read_b128 v[186:189], v215 offset:1024
	ds_read_b128 v[190:193], v215 offset:2048
	ds_read_b128 v[216:219], v215 offset:3072
	ds_read_b128 v[220:223], v215 offset:4096
	ds_read_b128 v[224:227], v215 offset:5120
	ds_read_b128 v[228:231], v215 offset:6144
	ds_read_b128 v[232:235], v215 offset:7168
	global_load_lds_dwordx4 v[194:195], off
	v_lshl_add_u64 v[194:195], s[40:41], 0, v[180:181]
	s_add_i32 m0, s97, 0xe000
	s_nop 0
	global_load_lds_dwordx4 v[194:195], off
	s_waitcnt vmcnt(8)
	s_waitcnt lgkmcnt(0)
	s_barrier
	s_setprio 1
	s_waitcnt lgkmcnt(0)
	v_mfma_f32_16x16x32_bf16 v[158:161], v[32:35], v[182:185], 0
	v_mfma_f32_16x16x32_bf16 v[154:157], v[40:43], v[182:185], 0
	v_mfma_f32_16x16x32_bf16 v[138:141], v[40:43], v[190:193], 0
	v_mfma_f32_16x16x32_bf16 v[142:145], v[32:35], v[190:193], 0
	v_mfma_f32_16x16x32_bf16 v[126:129], v[32:35], v[220:223], 0
	v_mfma_f32_16x16x32_bf16 v[122:125], v[40:43], v[220:223], 0
	v_mfma_f32_16x16x32_bf16 v[106:109], v[40:43], v[228:231], 0
	v_mfma_f32_16x16x32_bf16 v[110:113], v[32:35], v[228:231], 0
	v_mfma_f32_16x16x32_bf16 v[158:161], v[36:39], v[186:189], v[158:161]
	v_mfma_f32_16x16x32_bf16 v[154:157], v[44:47], v[186:189], v[154:157]
	v_mfma_f32_16x16x32_bf16 v[138:141], v[44:47], v[216:219], v[138:141]
	v_mfma_f32_16x16x32_bf16 v[142:145], v[36:39], v[216:219], v[142:145]
	v_mfma_f32_16x16x32_bf16 v[126:129], v[36:39], v[224:227], v[126:129]
	v_mfma_f32_16x16x32_bf16 v[122:125], v[44:47], v[224:227], v[122:125]
	v_mfma_f32_16x16x32_bf16 v[106:109], v[44:47], v[232:235], v[106:109]
	v_mfma_f32_16x16x32_bf16 v[110:113], v[36:39], v[232:235], v[110:113]
	v_mfma_f32_16x16x32_bf16 v[150:153], v[90:93], v[182:185], 0
	v_mfma_f32_16x16x32_bf16 v[146:149], v[98:101], v[182:185], 0
	v_mfma_f32_16x16x32_bf16 v[130:133], v[98:101], v[190:193], 0
	v_mfma_f32_16x16x32_bf16 v[134:137], v[90:93], v[190:193], 0
	v_mfma_f32_16x16x32_bf16 v[118:121], v[90:93], v[220:223], 0
	v_mfma_f32_16x16x32_bf16 v[114:117], v[98:101], v[220:223], 0
	v_mfma_f32_16x16x32_bf16 v[82:85], v[98:101], v[228:231], 0
	v_mfma_f32_16x16x32_bf16 v[86:89], v[90:93], v[228:231], 0
	v_mfma_f32_16x16x32_bf16 v[150:153], v[94:97], v[186:189], v[150:153]
	v_mfma_f32_16x16x32_bf16 v[146:149], v[102:105], v[186:189], v[146:149]
	v_mfma_f32_16x16x32_bf16 v[130:133], v[102:105], v[216:219], v[130:133]
	v_mfma_f32_16x16x32_bf16 v[134:137], v[94:97], v[216:219], v[134:137]
	v_mfma_f32_16x16x32_bf16 v[118:121], v[94:97], v[224:227], v[118:121]
	v_mfma_f32_16x16x32_bf16 v[114:117], v[102:105], v[224:227], v[114:117]
	v_mfma_f32_16x16x32_bf16 v[82:85], v[102:105], v[232:235], v[82:85]
	v_mfma_f32_16x16x32_bf16 v[86:89], v[94:97], v[232:235], v[86:89]
	s_setprio 0
	s_barrier
	s_add_i32 s14, s16, s95
	v_lshl_add_u64 v[194:195], s[42:43], 0, v[174:175]
	s_mov_b32 m0, s14
	s_nop 0
	global_load_lds_dwordx4 v[194:195], off
	s_add_i32 m0, s14, 0x2000
	s_add_u32 s14, s42, 0x40000
	v_lshl_add_u64 v[236:237], s[42:43], 0, v[176:177]
	s_addc_u32 s15, s43, 0
	s_add_i32 s16, s17, s95
	global_load_lds_dwordx4 v[236:237], off
	v_lshl_add_u64 v[238:239], s[14:15], 0, v[174:175]
	s_mov_b32 m0, s16
	v_lshl_add_u64 v[240:241], s[70:71], 0, v[176:177]
	global_load_lds_dwordx4 v[238:239], off
	v_lshl_add_u64 v[238:239], s[14:15], 0, v[176:177]
	s_add_i32 m0, s16, 0x2000
	s_nop 0
	global_load_lds_dwordx4 v[238:239], off
	v_lshl_add_u64 v[238:239], s[70:71], 0, v[174:175]
	s_mov_b32 m0, s97
	s_nop 0
	global_load_lds_dwordx4 v[238:239], off
	s_mov_b32 m0, s98
	s_nop 0
	global_load_lds_dwordx4 v[240:241], off
	ds_read_b128 v[182:185], v215 offset:16384
	ds_read_b128 v[186:189], v215 offset:17408
	ds_read_b128 v[190:193], v215 offset:18432
	ds_read_b128 v[216:219], v215 offset:19456
	ds_read_b128 v[220:223], v215 offset:20480
	ds_read_b128 v[224:227], v215 offset:21504
	ds_read_b128 v[228:231], v215 offset:22528
	ds_read_b128 v[232:235], v215 offset:23552
	s_waitcnt vmcnt(8)
	s_waitcnt lgkmcnt(0)
	s_barrier
; #define PG8_STAGE(bufoff, gbase, voff) do { _Pragma("unroll") for (int _i = 0; _i < 2; ++_i) \
;         __builtin_amdgcn_global_load_lds((const unsigned*)((const char*)(gbase) + (voff)[_i]), (PG8_LAS unsigned*)(lds + (bufoff) + ldsw + _i * 8192), 16, 0, 0); } while (0)
; #define PG8_LDA(dst, b, h) do { _Pragma("unroll") for (int m = 0; m < 4; ++m) _Pragma("unroll") for (int k = 0; k < 2; ++k) dst[m][k] = *(const PG8_LAS bf16x8*)(lds + PG8_SA(b, h) + aoff + m * 2048 + k * 1024); } while (0)
; #define PG8_LDB(dst, b, h) do { _Pragma("unroll") for (int n = 0; n < 2; ++n) _Pragma("unroll") for (int k = 0; k < 2; ++k) dst[n][k] = *(const PG8_LAS bf16x8*)(lds + PG8_SB(b, h) + boff + n * 2048 + k * 1024); } while (0)
; #define PG8_MMA(ai, bj, At, Bt) do { __builtin_amdgcn_s_setprio(1); _Pragma("unroll") for (int m = 0; m < 4; ++m) _Pragma("unroll") for (int n = 0; n < 2; ++n) _Pragma("unroll") for (int k = 0; k < 2; ++k) \
;         acc[ai][bj][m][n] = __builtin_amdgcn_mfma_f32_16x16x32_bf16(Bt[n][k], At[m][k], acc[ai][bj][m][n], 0, 0, 0); __builtin_amdgcn_s_setprio(0); } while (0)
; #define PG8_WAIT_V(n) asm volatile("s_waitcnt vmcnt(" #n ")" ::: "memory")
; #define PG8_WAIT_L(n) asm volatile("s_waitcnt lgkmcnt(" #n ")" ::: "memory")
; #define PG8_BAR __builtin_amdgcn_s_barrier()
; #define PG8_SCHED __builtin_amdgcn_sched_barrier(0)
; template <class Epi, class Sched, bool ALIGN_EPI = false, bool SP2 = false>
; __device__ __forceinline__ void gemm_phase(PG8_LAS unsigned char* lds, const Gemm g, const Sched& S, const Epi& E) {
;     ...
;             PG8_WAIT_V(8); PG8_WAIT_L(0); PG8_BAR; PG8_MMA(1, 0, At, B0); PG8_MMA(1, 1, At, B1); PG8_BAR; PG8_SCHED;
;             PG8_LDB(B0, 1, 0); PG8_LDB(B1, 1, 1); PG8_SCHED; PG8_LDA(At, 1, 0); PG8_STAGE(PG8_SA(0, 1), a2 + hstep, voffA);
;             PG8_WAIT_V(8); PG8_WAIT_L(0); PG8_BAR; PG8_MMA(0, 0, At, B0); PG8_MMA(0, 1, At, B1); PG8_BAR; PG8_SCHED;
	s_setprio 1
	s_waitcnt lgkmcnt(0)
	v_mfma_f32_16x16x32_bf16 v[76:79], v[32:35], v[182:185], 0
	v_mfma_f32_16x16x32_bf16 v[72:75], v[40:43], v[182:185], 0
	v_mfma_f32_16x16x32_bf16 v[56:59], v[40:43], v[190:193], 0
	v_mfma_f32_16x16x32_bf16 v[60:63], v[32:35], v[190:193], 0
	v_mfma_f32_16x16x32_bf16 v[28:31], v[32:35], v[220:223], 0
	v_mfma_f32_16x16x32_bf16 v[24:27], v[40:43], v[220:223], 0
	v_mfma_f32_16x16x32_bf16 v[8:11], v[40:43], v[228:231], 0
	v_mfma_f32_16x16x32_bf16 v[12:15], v[32:35], v[228:231], 0
	v_mfma_f32_16x16x32_bf16 v[76:79], v[36:39], v[186:189], v[76:79]
	v_mfma_f32_16x16x32_bf16 v[72:75], v[44:47], v[186:189], v[72:75]
	v_mfma_f32_16x16x32_bf16 v[56:59], v[44:47], v[216:219], v[56:59]
	v_mfma_f32_16x16x32_bf16 v[60:63], v[36:39], v[216:219], v[60:63]
	v_mfma_f32_16x16x32_bf16 v[28:31], v[36:39], v[224:227], v[28:31]
	v_mfma_f32_16x16x32_bf16 v[24:27], v[44:47], v[224:227], v[24:27]
	v_mfma_f32_16x16x32_bf16 v[8:11], v[44:47], v[232:235], v[8:11]
	v_mfma_f32_16x16x32_bf16 v[12:15], v[36:39], v[232:235], v[12:15]
	v_mfma_f32_16x16x32_bf16 v[20:23], v[90:93], v[220:223], 0
	v_mfma_f32_16x16x32_bf16 v[16:19], v[98:101], v[220:223], 0
	v_mfma_f32_16x16x32_bf16 v[0:3], v[98:101], v[228:231], 0
	v_mfma_f32_16x16x32_bf16 v[4:7], v[90:93], v[228:231], 0
	v_mfma_f32_16x16x32_bf16 v[32:35], v[90:93], v[182:185], 0
	v_mfma_f32_16x16x32_bf16 v[36:39], v[98:101], v[182:185], 0
	v_mfma_f32_16x16x32_bf16 v[44:47], v[98:101], v[190:193], 0
	v_mfma_f32_16x16x32_bf16 v[40:43], v[90:93], v[190:193], 0
	v_mfma_f32_16x16x32_bf16 v[20:23], v[94:97], v[224:227], v[20:23]
	v_mfma_f32_16x16x32_bf16 v[16:19], v[102:105], v[224:227], v[16:19]
	v_mfma_f32_16x16x32_bf16 v[0:3], v[102:105], v[232:235], v[0:3]
	v_mfma_f32_16x16x32_bf16 v[4:7], v[94:97], v[232:235], v[4:7]
	v_mfma_f32_16x16x32_bf16 v[32:35], v[94:97], v[186:189], v[32:35]
	v_mfma_f32_16x16x32_bf16 v[36:39], v[102:105], v[186:189], v[36:39]
	v_mfma_f32_16x16x32_bf16 v[44:47], v[102:105], v[216:219], v[44:47]
	v_mfma_f32_16x16x32_bf16 v[40:43], v[94:97], v[216:219], v[40:43]
	s_setprio 0
	s_barrier
	s_add_i32 s16, 0, 0x18000
	s_add_i32 s17, 0, 0x1c000
	v_add_u32_e32 v68, s16, v214
	v_add_u32_e32 v102, s17, v214
	s_add_u32 s14, s70, 0x40000
	s_addc_u32 s15, s71, 0
	s_mov_b32 m0, s99
	v_lshl_add_u64 v[242:243], s[14:15], 0, v[174:175]
	global_load_lds_dwordx4 v[242:243], off
	v_lshl_add_u64 v[242:243], s[14:15], 0, v[176:177]
	s_mov_b32 m0, s94
	s_nop 0
	global_load_lds_dwordx4 v[242:243], off
	ds_read_b128 v[48:51], v68
	ds_read_b128 v[52:55], v68 offset:1024
	ds_read_b128 v[64:67], v68 offset:2048
	ds_read_b128 v[68:71], v68 offset:3072
	ds_read_b128 v[90:93], v102
	ds_read_b128 v[94:97], v102 offset:1024
	ds_read_b128 v[98:101], v102 offset:2048
	ds_read_b128 v[102:105], v102 offset:3072
	ds_read_b128 v[182:185], v215 offset:32768
	ds_read_b128 v[186:189], v215 offset:33792
	ds_read_b128 v[190:193], v215 offset:34816
	ds_read_b128 v[216:219], v215 offset:35840
	ds_read_b128 v[220:223], v215 offset:36864
	ds_read_b128 v[224:227], v215 offset:37888
	ds_read_b128 v[228:231], v215 offset:38912
	ds_read_b128 v[232:235], v215 offset:39936
	s_waitcnt vmcnt(8)
	s_waitcnt lgkmcnt(0)
	s_barrier
	s_setprio 1
	s_waitcnt lgkmcnt(0)
	v_mfma_f32_16x16x32_bf16 v[158:161], v[48:51], v[182:185], v[158:161]
	v_mfma_f32_16x16x32_bf16 v[154:157], v[64:67], v[182:185], v[154:157]
	v_mfma_f32_16x16x32_bf16 v[138:141], v[64:67], v[190:193], v[138:141]
	v_mfma_f32_16x16x32_bf16 v[142:145], v[48:51], v[190:193], v[142:145]
	v_mfma_f32_16x16x32_bf16 v[126:129], v[48:51], v[220:223], v[126:129]
	v_mfma_f32_16x16x32_bf16 v[122:125], v[64:67], v[220:223], v[122:125]
	v_mfma_f32_16x16x32_bf16 v[106:109], v[64:67], v[228:231], v[106:109]
	v_mfma_f32_16x16x32_bf16 v[110:113], v[48:51], v[228:231], v[110:113]
	v_mfma_f32_16x16x32_bf16 v[158:161], v[52:55], v[186:189], v[158:161]
	v_mfma_f32_16x16x32_bf16 v[154:157], v[68:71], v[186:189], v[154:157]
	v_mfma_f32_16x16x32_bf16 v[138:141], v[68:71], v[216:219], v[138:141]
	v_mfma_f32_16x16x32_bf16 v[142:145], v[52:55], v[216:219], v[142:145]
	v_mfma_f32_16x16x32_bf16 v[126:129], v[52:55], v[224:227], v[126:129]
	v_mfma_f32_16x16x32_bf16 v[122:125], v[68:71], v[224:227], v[122:125]
	v_mfma_f32_16x16x32_bf16 v[106:109], v[68:71], v[232:235], v[106:109]
	v_mfma_f32_16x16x32_bf16 v[110:113], v[52:55], v[232:235], v[110:113]
	v_mfma_f32_16x16x32_bf16 v[150:153], v[90:93], v[182:185], v[150:153]
	v_mfma_f32_16x16x32_bf16 v[146:149], v[98:101], v[182:185], v[146:149]
	v_mfma_f32_16x16x32_bf16 v[130:133], v[98:101], v[190:193], v[130:133]
	v_mfma_f32_16x16x32_bf16 v[134:137], v[90:93], v[190:193], v[134:137]
	v_mfma_f32_16x16x32_bf16 v[118:121], v[90:93], v[220:223], v[118:121]
	v_mfma_f32_16x16x32_bf16 v[114:117], v[98:101], v[220:223], v[114:117]
	v_mfma_f32_16x16x32_bf16 v[82:85], v[98:101], v[228:231], v[82:85]
	v_mfma_f32_16x16x32_bf16 v[86:89], v[90:93], v[228:231], v[86:89]
	v_mfma_f32_16x16x32_bf16 v[150:153], v[94:97], v[186:189], v[150:153]
	v_mfma_f32_16x16x32_bf16 v[146:149], v[102:105], v[186:189], v[146:149]
	v_mfma_f32_16x16x32_bf16 v[130:133], v[102:105], v[216:219], v[130:133]
	v_mfma_f32_16x16x32_bf16 v[134:137], v[94:97], v[216:219], v[134:137]
	v_mfma_f32_16x16x32_bf16 v[118:121], v[94:97], v[224:227], v[118:121]
	v_mfma_f32_16x16x32_bf16 v[114:117], v[102:105], v[224:227], v[114:117]
	v_mfma_f32_16x16x32_bf16 v[82:85], v[102:105], v[232:235], v[82:85]
	v_mfma_f32_16x16x32_bf16 v[86:89], v[94:97], v[232:235], v[86:89]
	s_setprio 0
	s_barrier
; #define PG8_STAGE(bufoff, gbase, voff) do { _Pragma("unroll") for (int _i = 0; _i < 2; ++_i) \
;         __builtin_amdgcn_global_load_lds((const unsigned*)((const char*)(gbase) + (voff)[_i]), (PG8_LAS unsigned*)(lds + (bufoff) + ldsw + _i * 8192), 16, 0, 0); } while (0)
; #define PG8_LDA(dst, b, h) do { _Pragma("unroll") for (int m = 0; m < 4; ++m) _Pragma("unroll") for (int k = 0; k < 2; ++k) dst[m][k] = *(const PG8_LAS bf16x8*)(lds + PG8_SA(b, h) + aoff + m * 2048 + k * 1024); } while (0)
; #define PG8_LDB(dst, b, h) do { _Pragma("unroll") for (int n = 0; n < 2; ++n) _Pragma("unroll") for (int k = 0; k < 2; ++k) dst[n][k] = *(const PG8_LAS bf16x8*)(lds + PG8_SB(b, h) + boff + n * 2048 + k * 1024); } while (0)
; #define PG8_BAR __builtin_amdgcn_s_barrier()
; template <class Epi, class Sched, bool ALIGN_EPI = false, bool SP2 = false>
; __device__ __forceinline__ void gemm_phase(PG8_LAS unsigned char* lds, const Gemm g, const Sched& S, const Epi& E) {
;     ...
;             const bool last = (t == nt - 2);
;             const char* a1 = cA + (size_t)(t + 1) * kstep;
;             const char* a2 = last ? nA : cA + (size_t)(t + 2) * kstep; const char* b2 = last ? nB : cB + (size_t)(t + 2) * kstep;
;             const char* a3 = a2 + kstep; const char* b3 = b2 + kstep;
;             if (last && has_next) S.a_ready(nxt);
;             if constexpr (SP2) {
;             PG8_LDB(B0, 0, 0); PG8_LDB(B1, 0, 1); PG8_SCHED; PG8_LDA(At, 0, 0); PG8_STAGE(PG8_SA(1, 1), a1 + hstep, voffA);
;             PG8_WAIT_V(8); PG8_WAIT_L(0); PG8_BAR; PG8_MMA(0, 0, At, B0); PG8_MMA(0, 1, At, B1); PG8_BAR; PG8_SCHED;
;             PG8_LDA(At, 0, 1); PG8_STAGE(PG8_SB(0, 0), b2, voffB); PG8_STAGE(PG8_SB(0, 1), b2 + hstep, voffB); PG8_STAGE(PG8_SA(0, 0), a2, voffA);
;             PG8_WAIT_V(8); PG8_WAIT_L(0); PG8_BAR; PG8_MMA(1, 0, At, B0); PG8_MMA(1, 1, At, B1); PG8_BAR; PG8_SCHED;
;             PG8_LDB(B0, 1, 0); PG8_LDB(B1, 1, 1); PG8_SCHED; PG8_LDA(At, 1, 0); PG8_STAGE(PG8_SA(0, 1), a2 + hstep, voffA);
;             PG8_WAIT_V(8); PG8_WAIT_L(0); PG8_BAR; PG8_MMA(0, 0, At, B0); PG8_MMA(0, 1, At, B1); PG8_BAR; PG8_SCHED;
;             PG8_LDA(At, 1, 1); PG8_STAGE(PG8_SB(1, 0), b3, voffB); PG8_STAGE(PG8_SB(1, 1), b3 + hstep, voffB); PG8_STAGE(PG8_SA(1, 0), a3, voffA);
;             PG8_WAIT_V(8); PG8_WAIT_L(0); PG8_BAR; PG8_MMA(1, 0, At, B0); PG8_MMA(1, 1, At, B1); PG8_BAR; PG8_SCHED;
	s_add_i32 s14, s16, s95
	v_lshl_add_u64 v[194:195], v[194:195], 0, s[0:1]
	s_mov_b32 m0, s14
	s_nop 0
	global_load_lds_dwordx4 v[194:195], off
	s_add_i32 m0, s14, 0x2000
	s_add_u32 s14, s42, 0x40080
	v_lshl_add_u64 v[194:195], v[236:237], 0, s[0:1]
	s_addc_u32 s15, s43, 0
	s_add_i32 s16, s17, s95
	global_load_lds_dwordx4 v[194:195], off
	v_lshl_add_u64 v[194:195], s[14:15], 0, v[174:175]
	s_mov_b32 m0, s16
	s_nop 0
	global_load_lds_dwordx4 v[194:195], off
	v_lshl_add_u64 v[194:195], s[14:15], 0, v[176:177]
	s_add_i32 m0, s16, 0x2000
	s_nop 0
	global_load_lds_dwordx4 v[194:195], off
	v_lshl_add_u64 v[194:195], v[238:239], 0, s[0:1]
	s_mov_b32 m0, s44
	s_nop 0
	global_load_lds_dwordx4 v[194:195], off
	v_lshl_add_u64 v[194:195], v[240:241], 0, s[0:1]
	s_mov_b32 m0, s45
	s_nop 0
	global_load_lds_dwordx4 v[194:195], off
	ds_read_b128 v[182:185], v215 offset:49152
	ds_read_b128 v[186:189], v215 offset:50176
	ds_read_b128 v[190:193], v215 offset:51200
	ds_read_b128 v[216:219], v215 offset:52224
	ds_read_b128 v[220:223], v215 offset:53248
	ds_read_b128 v[224:227], v215 offset:54272
	ds_read_b128 v[228:231], v215 offset:55296
	ds_read_b128 v[232:235], v215 offset:56320
	s_waitcnt vmcnt(8)
	s_waitcnt lgkmcnt(0)
	s_barrier
	s_setprio 1
	s_waitcnt lgkmcnt(0)
	v_mfma_f32_16x16x32_bf16 v[76:79], v[48:51], v[182:185], v[76:79]
	v_mfma_f32_16x16x32_bf16 v[72:75], v[64:67], v[182:185], v[72:75]
	v_mfma_f32_16x16x32_bf16 v[56:59], v[64:67], v[190:193], v[56:59]
	v_mfma_f32_16x16x32_bf16 v[60:63], v[48:51], v[190:193], v[60:63]
	v_mfma_f32_16x16x32_bf16 v[28:31], v[48:51], v[220:223], v[28:31]
	v_mfma_f32_16x16x32_bf16 v[24:27], v[64:67], v[220:223], v[24:27]
	v_mfma_f32_16x16x32_bf16 v[8:11], v[64:67], v[228:231], v[8:11]
	v_mfma_f32_16x16x32_bf16 v[12:15], v[48:51], v[228:231], v[12:15]
	v_mfma_f32_16x16x32_bf16 v[76:79], v[52:55], v[186:189], v[76:79]
	v_mfma_f32_16x16x32_bf16 v[72:75], v[68:71], v[186:189], v[72:75]
	v_mfma_f32_16x16x32_bf16 v[56:59], v[68:71], v[216:219], v[56:59]
	v_mfma_f32_16x16x32_bf16 v[60:63], v[52:55], v[216:219], v[60:63]
	v_mfma_f32_16x16x32_bf16 v[28:31], v[52:55], v[224:227], v[28:31]
	v_mfma_f32_16x16x32_bf16 v[24:27], v[68:71], v[224:227], v[24:27]
	v_mfma_f32_16x16x32_bf16 v[8:11], v[68:71], v[232:235], v[8:11]
	v_mfma_f32_16x16x32_bf16 v[12:15], v[52:55], v[232:235], v[12:15]
	v_mfma_f32_16x16x32_bf16 v[32:35], v[90:93], v[182:185], v[32:35]
	v_mfma_f32_16x16x32_bf16 v[68:71], v[94:97], v[186:189], v[32:35]
	v_mfma_f32_16x16x32_bf16 v[32:35], v[98:101], v[182:185], v[36:39]
	v_mfma_f32_16x16x32_bf16 v[64:67], v[102:105], v[186:189], v[32:35]
	v_mfma_f32_16x16x32_bf16 v[32:35], v[90:93], v[190:193], v[40:43]
	v_mfma_f32_16x16x32_bf16 v[52:55], v[94:97], v[216:219], v[32:35]
	v_mfma_f32_16x16x32_bf16 v[32:35], v[98:101], v[190:193], v[44:47]
	v_mfma_f32_16x16x32_bf16 v[20:23], v[90:93], v[220:223], v[20:23]
	v_mfma_f32_16x16x32_bf16 v[16:19], v[98:101], v[220:223], v[16:19]
	v_mfma_f32_16x16x32_bf16 v[4:7], v[90:93], v[228:231], v[4:7]
	v_mfma_f32_16x16x32_bf16 v[0:3], v[98:101], v[228:231], v[0:3]
	v_mfma_f32_16x16x32_bf16 v[48:51], v[102:105], v[216:219], v[32:35]
	v_mfma_f32_16x16x32_bf16 v[20:23], v[94:97], v[224:227], v[20:23]
	v_mfma_f32_16x16x32_bf16 v[16:19], v[102:105], v[224:227], v[16:19]
	v_mfma_f32_16x16x32_bf16 v[0:3], v[102:105], v[232:235], v[0:3]
	v_mfma_f32_16x16x32_bf16 v[4:7], v[94:97], v[232:235], v[4:7]
	s_setprio 0
	s_barrier
	s_add_i32 s13, s13, 2
	s_add_u32 s40, s40, 0x100
	s_addc_u32 s41, s41, 0
	s_add_u32 s11, s11, 0x100
	s_addc_u32 s12, s12, 0
	s_cmp_gt_u32 s13, 13
	s_cbranch_scc1 .Lpeel_done_1
.LBB0_316:
	s_add_u32 s14, s40, 0xfffc0080
	s_addc_u32 s15, s41, -1
	s_add_i32 s16, 0, 0x10000
	s_cmp_eq_u32 s13, 12
	s_cselect_b32 s71, s3, s15
	s_cselect_b32 s70, s8, s14
	s_cselect_b32 s43, s9, s12
	s_cselect_b32 s42, s10, s11
	s_add_i32 s17, 0, 0x14000
	s_waitcnt lgkmcnt(0)
	v_add_u32_e32 v44, s16, v214
	v_add_u32_e32 v102, s17, v214
	ds_read_b128 v[32:35], v44
	ds_read_b128 v[36:39], v44 offset:1024
	ds_read_b128 v[40:43], v44 offset:2048
	ds_read_b128 v[44:47], v44 offset:3072
	ds_read_b128 v[90:93], v102
	ds_read_b128 v[94:97], v102 offset:1024
	ds_read_b128 v[98:101], v102 offset:2048
	ds_read_b128 v[102:105], v102 offset:3072
	v_lshl_add_u64 v[194:195], s[40:41], 0, v[178:179]
	s_add_i32 m0, s97, 0xc000
	ds_read_b128 v[182:185], v215
	ds_read_b128 v[186:189], v215 offset:1024
	ds_read_b128 v[190:193], v215 offset:2048
	ds_read_b128 v[216:219], v215 offset:3072
	ds_read_b128 v[220:223], v215 offset:4096
	ds_read_b128 v[224:227], v215 offset:5120
	ds_read_b128 v[228:231], v215 offset:6144
	ds_read_b128 v[232:235], v215 offset:7168
	global_load_lds_dwordx4 v[194:195], off
	v_lshl_add_u64 v[194:195], s[40:41], 0, v[180:181]
	s_add_i32 m0, s97, 0xe000
	s_nop 0
	global_load_lds_dwordx4 v[194:195], off
	s_waitcnt vmcnt(8)
	s_waitcnt lgkmcnt(0)
	s_barrier
; #define PG8_STAGE(bufoff, gbase, voff) do { _Pragma("unroll") for (int _i = 0; _i < 2; ++_i) \
;         __builtin_amdgcn_global_load_lds((const unsigned*)((const char*)(gbase) + (voff)[_i]), (PG8_LAS unsigned*)(lds + (bufoff) + ldsw + _i * 8192), 16, 0, 0); } while (0)
; #define PG8_LDA(dst, b, h) do { _Pragma("unroll") for (int m = 0; m < 4; ++m) _Pragma("unroll") for (int k = 0; k < 2; ++k) dst[m][k] = *(const PG8_LAS bf16x8*)(lds + PG8_SA(b, h) + aoff + m * 2048 + k * 1024); } while (0)
; #define PG8_MMA(ai, bj, At, Bt) do { __builtin_amdgcn_s_setprio(1); _Pragma("unroll") for (int m = 0; m < 4; ++m) _Pragma("unroll") for (int n = 0; n < 2; ++n) _Pragma("unroll") for (int k = 0; k < 2; ++k) \
;         acc[ai][bj][m][n] = __builtin_amdgcn_mfma_f32_16x16x32_bf16(Bt[n][k], At[m][k], acc[ai][bj][m][n], 0, 0, 0); __builtin_amdgcn_s_setprio(0); } while (0)
; #define PG8_WAIT_V(n) asm volatile("s_waitcnt vmcnt(" #n ")" ::: "memory")
; #define PG8_WAIT_L(n) asm volatile("s_waitcnt lgkmcnt(" #n ")" ::: "memory")
; #define PG8_BAR __builtin_amdgcn_s_barrier()
; #define PG8_SCHED __builtin_amdgcn_sched_barrier(0)
; template <class Epi, class Sched, bool ALIGN_EPI = false, bool SP2 = false>
; __device__ __forceinline__ void gemm_phase(PG8_LAS unsigned char* lds, const Gemm g, const Sched& S, const Epi& E) {
;     ...
;             PG8_WAIT_V(8); PG8_WAIT_L(0); PG8_BAR; PG8_MMA(0, 0, At, B0); PG8_MMA(0, 1, At, B1); PG8_BAR; PG8_SCHED;
;             PG8_LDA(At, 0, 1); PG8_STAGE(PG8_SB(0, 0), b2, voffB); PG8_STAGE(PG8_SB(0, 1), b2 + hstep, voffB); PG8_STAGE(PG8_SA(0, 0), a2, voffA);
;             PG8_WAIT_V(8); PG8_WAIT_L(0); PG8_BAR; PG8_MMA(1, 0, At, B0); PG8_MMA(1, 1, At, B1); PG8_BAR; PG8_SCHED;
	s_setprio 1
	s_waitcnt lgkmcnt(0)
	v_mfma_f32_16x16x32_bf16 v[158:161], v[32:35], v[182:185], v[158:161]
	v_mfma_f32_16x16x32_bf16 v[154:157], v[40:43], v[182:185], v[154:157]
	v_mfma_f32_16x16x32_bf16 v[138:141], v[40:43], v[190:193], v[138:141]
	v_mfma_f32_16x16x32_bf16 v[142:145], v[32:35], v[190:193], v[142:145]
	v_mfma_f32_16x16x32_bf16 v[126:129], v[32:35], v[220:223], v[126:129]
	v_mfma_f32_16x16x32_bf16 v[122:125], v[40:43], v[220:223], v[122:125]
	v_mfma_f32_16x16x32_bf16 v[106:109], v[40:43], v[228:231], v[106:109]
	v_mfma_f32_16x16x32_bf16 v[110:113], v[32:35], v[228:231], v[110:113]
	v_mfma_f32_16x16x32_bf16 v[158:161], v[36:39], v[186:189], v[158:161]
	v_mfma_f32_16x16x32_bf16 v[154:157], v[44:47], v[186:189], v[154:157]
	v_mfma_f32_16x16x32_bf16 v[138:141], v[44:47], v[216:219], v[138:141]
	v_mfma_f32_16x16x32_bf16 v[142:145], v[36:39], v[216:219], v[142:145]
	v_mfma_f32_16x16x32_bf16 v[126:129], v[36:39], v[224:227], v[126:129]
	v_mfma_f32_16x16x32_bf16 v[122:125], v[44:47], v[224:227], v[122:125]
	v_mfma_f32_16x16x32_bf16 v[106:109], v[44:47], v[232:235], v[106:109]
	v_mfma_f32_16x16x32_bf16 v[110:113], v[36:39], v[232:235], v[110:113]
	v_mfma_f32_16x16x32_bf16 v[150:153], v[90:93], v[182:185], v[150:153]
	v_mfma_f32_16x16x32_bf16 v[146:149], v[98:101], v[182:185], v[146:149]
	v_mfma_f32_16x16x32_bf16 v[130:133], v[98:101], v[190:193], v[130:133]
	v_mfma_f32_16x16x32_bf16 v[134:137], v[90:93], v[190:193], v[134:137]
	v_mfma_f32_16x16x32_bf16 v[118:121], v[90:93], v[220:223], v[118:121]
	v_mfma_f32_16x16x32_bf16 v[114:117], v[98:101], v[220:223], v[114:117]
	v_mfma_f32_16x16x32_bf16 v[82:85], v[98:101], v[228:231], v[82:85]
	v_mfma_f32_16x16x32_bf16 v[86:89], v[90:93], v[228:231], v[86:89]
	v_mfma_f32_16x16x32_bf16 v[150:153], v[94:97], v[186:189], v[150:153]
	v_mfma_f32_16x16x32_bf16 v[146:149], v[102:105], v[186:189], v[146:149]
	v_mfma_f32_16x16x32_bf16 v[130:133], v[102:105], v[216:219], v[130:133]
	v_mfma_f32_16x16x32_bf16 v[134:137], v[94:97], v[216:219], v[134:137]
	v_mfma_f32_16x16x32_bf16 v[118:121], v[94:97], v[224:227], v[118:121]
	v_mfma_f32_16x16x32_bf16 v[114:117], v[102:105], v[224:227], v[114:117]
	v_mfma_f32_16x16x32_bf16 v[82:85], v[102:105], v[232:235], v[82:85]
	v_mfma_f32_16x16x32_bf16 v[86:89], v[94:97], v[232:235], v[86:89]
	s_setprio 0
	s_barrier
	s_add_i32 s14, s16, s95
	v_lshl_add_u64 v[194:195], s[42:43], 0, v[174:175]
	s_mov_b32 m0, s14
	s_nop 0
	global_load_lds_dwordx4 v[194:195], off
	s_add_i32 m0, s14, 0x2000
	s_add_u32 s14, s42, 0x40000
	v_lshl_add_u64 v[236:237], s[42:43], 0, v[176:177]
	s_addc_u32 s15, s43, 0
	s_add_i32 s16, s17, s95
	global_load_lds_dwordx4 v[236:237], off
	v_lshl_add_u64 v[238:239], s[14:15], 0, v[174:175]
	s_mov_b32 m0, s16
	v_lshl_add_u64 v[240:241], s[70:71], 0, v[176:177]
	global_load_lds_dwordx4 v[238:239], off
	v_lshl_add_u64 v[238:239], s[14:15], 0, v[176:177]
	s_add_i32 m0, s16, 0x2000
	s_nop 0
	global_load_lds_dwordx4 v[238:239], off
	v_lshl_add_u64 v[238:239], s[70:71], 0, v[174:175]
	s_mov_b32 m0, s97
	s_nop 0
	global_load_lds_dwordx4 v[238:239], off
	s_mov_b32 m0, s98
	s_nop 0
	global_load_lds_dwordx4 v[240:241], off
	ds_read_b128 v[182:185], v215 offset:16384
	ds_read_b128 v[186:189], v215 offset:17408
	ds_read_b128 v[190:193], v215 offset:18432
	ds_read_b128 v[216:219], v215 offset:19456
	ds_read_b128 v[220:223], v215 offset:20480
	ds_read_b128 v[224:227], v215 offset:21504
	ds_read_b128 v[228:231], v215 offset:22528
	ds_read_b128 v[232:235], v215 offset:23552
	s_waitcnt vmcnt(8)
	s_waitcnt lgkmcnt(0)
	s_barrier
	s_setprio 1
	s_waitcnt lgkmcnt(0)
	v_mfma_f32_16x16x32_bf16 v[76:79], v[32:35], v[182:185], v[76:79]
	v_mfma_f32_16x16x32_bf16 v[72:75], v[40:43], v[182:185], v[72:75]
	v_mfma_f32_16x16x32_bf16 v[56:59], v[40:43], v[190:193], v[56:59]
	v_mfma_f32_16x16x32_bf16 v[60:63], v[32:35], v[190:193], v[60:63]
	v_mfma_f32_16x16x32_bf16 v[28:31], v[32:35], v[220:223], v[28:31]
	v_mfma_f32_16x16x32_bf16 v[24:27], v[40:43], v[220:223], v[24:27]
	v_mfma_f32_16x16x32_bf16 v[8:11], v[40:43], v[228:231], v[8:11]
	v_mfma_f32_16x16x32_bf16 v[12:15], v[32:35], v[228:231], v[12:15]
	v_mfma_f32_16x16x32_bf16 v[76:79], v[36:39], v[186:189], v[76:79]
	v_mfma_f32_16x16x32_bf16 v[72:75], v[44:47], v[186:189], v[72:75]
	v_mfma_f32_16x16x32_bf16 v[56:59], v[44:47], v[216:219], v[56:59]
	v_mfma_f32_16x16x32_bf16 v[60:63], v[36:39], v[216:219], v[60:63]
	v_mfma_f32_16x16x32_bf16 v[28:31], v[36:39], v[224:227], v[28:31]
	v_mfma_f32_16x16x32_bf16 v[24:27], v[44:47], v[224:227], v[24:27]
	v_mfma_f32_16x16x32_bf16 v[8:11], v[44:47], v[232:235], v[8:11]
	v_mfma_f32_16x16x32_bf16 v[12:15], v[36:39], v[232:235], v[12:15]
	v_mfma_f32_16x16x32_bf16 v[20:23], v[90:93], v[220:223], v[20:23]
	v_mfma_f32_16x16x32_bf16 v[16:19], v[98:101], v[220:223], v[16:19]
	v_mfma_f32_16x16x32_bf16 v[0:3], v[98:101], v[228:231], v[0:3]
	v_mfma_f32_16x16x32_bf16 v[4:7], v[90:93], v[228:231], v[4:7]
	v_mfma_f32_16x16x32_bf16 v[32:35], v[90:93], v[182:185], v[68:71]
	v_mfma_f32_16x16x32_bf16 v[36:39], v[98:101], v[182:185], v[64:67]
	v_mfma_f32_16x16x32_bf16 v[44:47], v[98:101], v[190:193], v[48:51]
	v_mfma_f32_16x16x32_bf16 v[40:43], v[90:93], v[190:193], v[52:55]
	v_mfma_f32_16x16x32_bf16 v[20:23], v[94:97], v[224:227], v[20:23]
	v_mfma_f32_16x16x32_bf16 v[16:19], v[102:105], v[224:227], v[16:19]
	v_mfma_f32_16x16x32_bf16 v[0:3], v[102:105], v[232:235], v[0:3]
	v_mfma_f32_16x16x32_bf16 v[4:7], v[94:97], v[232:235], v[4:7]
	v_mfma_f32_16x16x32_bf16 v[32:35], v[94:97], v[186:189], v[32:35]
	v_mfma_f32_16x16x32_bf16 v[36:39], v[102:105], v[186:189], v[36:39]
	v_mfma_f32_16x16x32_bf16 v[44:47], v[102:105], v[216:219], v[44:47]
	v_mfma_f32_16x16x32_bf16 v[40:43], v[94:97], v[216:219], v[40:43]
	s_setprio 0
	s_barrier
; #define PG8_STAGE(bufoff, gbase, voff) do { _Pragma("unroll") for (int _i = 0; _i < 2; ++_i) \
;         __builtin_amdgcn_global_load_lds((const unsigned*)((const char*)(gbase) + (voff)[_i]), (PG8_LAS unsigned*)(lds + (bufoff) + ldsw + _i * 8192), 16, 0, 0); } while (0)
; #define PG8_LDA(dst, b, h) do { _Pragma("unroll") for (int m = 0; m < 4; ++m) _Pragma("unroll") for (int k = 0; k < 2; ++k) dst[m][k] = *(const PG8_LAS bf16x8*)(lds + PG8_SA(b, h) + aoff + m * 2048 + k * 1024); } while (0)
; #define PG8_LDB(dst, b, h) do { _Pragma("unroll") for (int n = 0; n < 2; ++n) _Pragma("unroll") for (int k = 0; k < 2; ++k) dst[n][k] = *(const PG8_LAS bf16x8*)(lds + PG8_SB(b, h) + boff + n * 2048 + k * 1024); } while (0)
; #define PG8_MMA(ai, bj, At, Bt) do { __builtin_amdgcn_s_setprio(1); _Pragma("unroll") for (int m = 0; m < 4; ++m) _Pragma("unroll") for (int n = 0; n < 2; ++n) _Pragma("unroll") for (int k = 0; k < 2; ++k) \
;         acc[ai][bj][m][n] = __builtin_amdgcn_mfma_f32_16x16x32_bf16(Bt[n][k], At[m][k], acc[ai][bj][m][n], 0, 0, 0); __builtin_amdgcn_s_setprio(0); } while (0)
; #define PG8_WAIT_V(n) asm volatile("s_waitcnt vmcnt(" #n ")" ::: "memory")
; #define PG8_WAIT_L(n) asm volatile("s_waitcnt lgkmcnt(" #n ")" ::: "memory")
; #define PG8_BAR __builtin_amdgcn_s_barrier()
; #define PG8_SCHED __builtin_amdgcn_sched_barrier(0)
; template <class Epi, class Sched, bool ALIGN_EPI = false, bool SP2 = false>
; __device__ __forceinline__ void gemm_phase(PG8_LAS unsigned char* lds, const Gemm g, const Sched& S, const Epi& E) {
;     ...
;             PG8_LDB(B0, 1, 0); PG8_LDB(B1, 1, 1); PG8_SCHED; PG8_LDA(At, 1, 0); PG8_STAGE(PG8_SA(0, 1), a2 + hstep, voffA);
;             PG8_WAIT_V(8); PG8_WAIT_L(0); PG8_BAR; PG8_MMA(0, 0, At, B0); PG8_MMA(0, 1, At, B1); PG8_BAR; PG8_SCHED;
;             PG8_LDA(At, 1, 1); PG8_STAGE(PG8_SB(1, 0), b3, voffB); PG8_STAGE(PG8_SB(1, 1), b3 + hstep, voffB); PG8_STAGE(PG8_SA(1, 0), a3, voffA);
;             PG8_WAIT_V(8); PG8_WAIT_L(0); PG8_BAR; PG8_MMA(1, 0, At, B0); PG8_MMA(1, 1, At, B1); PG8_BAR; PG8_SCHED;
	s_add_i32 s16, 0, 0x18000
	s_add_i32 s17, 0, 0x1c000
	v_add_u32_e32 v68, s16, v214
	v_add_u32_e32 v102, s17, v214
	s_add_u32 s14, s70, 0x40000
	s_addc_u32 s15, s71, 0
	s_mov_b32 m0, s99
	v_lshl_add_u64 v[242:243], s[14:15], 0, v[174:175]
	global_load_lds_dwordx4 v[242:243], off
	v_lshl_add_u64 v[242:243], s[14:15], 0, v[176:177]
	s_mov_b32 m0, s94
	s_nop 0
	global_load_lds_dwordx4 v[242:243], off
	ds_read_b128 v[48:51], v68
	ds_read_b128 v[52:55], v68 offset:1024
	ds_read_b128 v[64:67], v68 offset:2048
	ds_read_b128 v[68:71], v68 offset:3072
	ds_read_b128 v[90:93], v102
	ds_read_b128 v[94:97], v102 offset:1024
	ds_read_b128 v[98:101], v102 offset:2048
	ds_read_b128 v[102:105], v102 offset:3072
	ds_read_b128 v[182:185], v215 offset:32768
	ds_read_b128 v[186:189], v215 offset:33792
	ds_read_b128 v[190:193], v215 offset:34816
	ds_read_b128 v[216:219], v215 offset:35840
	ds_read_b128 v[220:223], v215 offset:36864
	ds_read_b128 v[224:227], v215 offset:37888
	ds_read_b128 v[228:231], v215 offset:38912
	ds_read_b128 v[232:235], v215 offset:39936
	s_waitcnt vmcnt(8)
	s_waitcnt lgkmcnt(0)
	s_barrier
	s_setprio 1
	s_waitcnt lgkmcnt(0)
	v_mfma_f32_16x16x32_bf16 v[158:161], v[48:51], v[182:185], v[158:161]
	v_mfma_f32_16x16x32_bf16 v[154:157], v[64:67], v[182:185], v[154:157]
	v_mfma_f32_16x16x32_bf16 v[138:141], v[64:67], v[190:193], v[138:141]
	v_mfma_f32_16x16x32_bf16 v[142:145], v[48:51], v[190:193], v[142:145]
	v_mfma_f32_16x16x32_bf16 v[126:129], v[48:51], v[220:223], v[126:129]
	v_mfma_f32_16x16x32_bf16 v[122:125], v[64:67], v[220:223], v[122:125]
	v_mfma_f32_16x16x32_bf16 v[106:109], v[64:67], v[228:231], v[106:109]
	v_mfma_f32_16x16x32_bf16 v[110:113], v[48:51], v[228:231], v[110:113]
	v_mfma_f32_16x16x32_bf16 v[158:161], v[52:55], v[186:189], v[158:161]
	v_mfma_f32_16x16x32_bf16 v[154:157], v[68:71], v[186:189], v[154:157]
	v_mfma_f32_16x16x32_bf16 v[138:141], v[68:71], v[216:219], v[138:141]
	v_mfma_f32_16x16x32_bf16 v[142:145], v[52:55], v[216:219], v[142:145]
	v_mfma_f32_16x16x32_bf16 v[126:129], v[52:55], v[224:227], v[126:129]
	v_mfma_f32_16x16x32_bf16 v[122:125], v[68:71], v[224:227], v[122:125]
	v_mfma_f32_16x16x32_bf16 v[106:109], v[68:71], v[232:235], v[106:109]
	v_mfma_f32_16x16x32_bf16 v[110:113], v[52:55], v[232:235], v[110:113]
	v_mfma_f32_16x16x32_bf16 v[150:153], v[90:93], v[182:185], v[150:153]
	v_mfma_f32_16x16x32_bf16 v[146:149], v[98:101], v[182:185], v[146:149]
	v_mfma_f32_16x16x32_bf16 v[130:133], v[98:101], v[190:193], v[130:133]
	v_mfma_f32_16x16x32_bf16 v[134:137], v[90:93], v[190:193], v[134:137]
	v_mfma_f32_16x16x32_bf16 v[118:121], v[90:93], v[220:223], v[118:121]
	v_mfma_f32_16x16x32_bf16 v[114:117], v[98:101], v[220:223], v[114:117]
	v_mfma_f32_16x16x32_bf16 v[82:85], v[98:101], v[228:231], v[82:85]
	v_mfma_f32_16x16x32_bf16 v[86:89], v[90:93], v[228:231], v[86:89]
	v_mfma_f32_16x16x32_bf16 v[150:153], v[94:97], v[186:189], v[150:153]
	v_mfma_f32_16x16x32_bf16 v[146:149], v[102:105], v[186:189], v[146:149]
	v_mfma_f32_16x16x32_bf16 v[130:133], v[102:105], v[216:219], v[130:133]
	v_mfma_f32_16x16x32_bf16 v[134:137], v[94:97], v[216:219], v[134:137]
	v_mfma_f32_16x16x32_bf16 v[118:121], v[94:97], v[224:227], v[118:121]
	v_mfma_f32_16x16x32_bf16 v[114:117], v[102:105], v[224:227], v[114:117]
	v_mfma_f32_16x16x32_bf16 v[82:85], v[102:105], v[232:235], v[82:85]
	v_mfma_f32_16x16x32_bf16 v[86:89], v[94:97], v[232:235], v[86:89]
	s_setprio 0
	s_barrier
	s_add_i32 s14, s16, s95
	v_lshl_add_u64 v[194:195], v[194:195], 0, s[0:1]
	s_mov_b32 m0, s14
	s_nop 0
	global_load_lds_dwordx4 v[194:195], off
	s_add_i32 m0, s14, 0x2000
	s_add_u32 s14, s42, 0x40080
	v_lshl_add_u64 v[194:195], v[236:237], 0, s[0:1]
	s_addc_u32 s15, s43, 0
	s_add_i32 s16, s17, s95
	global_load_lds_dwordx4 v[194:195], off
	v_lshl_add_u64 v[194:195], s[14:15], 0, v[174:175]
	s_mov_b32 m0, s16
	s_nop 0
	global_load_lds_dwordx4 v[194:195], off
	v_lshl_add_u64 v[194:195], s[14:15], 0, v[176:177]
	s_add_i32 m0, s16, 0x2000
	s_nop 0
	global_load_lds_dwordx4 v[194:195], off
	v_lshl_add_u64 v[194:195], v[238:239], 0, s[0:1]
	s_mov_b32 m0, s44
	s_nop 0
	global_load_lds_dwordx4 v[194:195], off
	v_lshl_add_u64 v[194:195], v[240:241], 0, s[0:1]
	s_mov_b32 m0, s45
	s_nop 0
	global_load_lds_dwordx4 v[194:195], off
	ds_read_b128 v[182:185], v215 offset:49152
	ds_read_b128 v[186:189], v215 offset:50176
	ds_read_b128 v[190:193], v215 offset:51200
	ds_read_b128 v[216:219], v215 offset:52224
	ds_read_b128 v[220:223], v215 offset:53248
	ds_read_b128 v[224:227], v215 offset:54272
	ds_read_b128 v[228:231], v215 offset:55296
	ds_read_b128 v[232:235], v215 offset:56320
	s_waitcnt vmcnt(8)
	s_waitcnt lgkmcnt(0)
	s_barrier
	s_setprio 1
	s_waitcnt lgkmcnt(0)
	v_mfma_f32_16x16x32_bf16 v[76:79], v[48:51], v[182:185], v[76:79]
	v_mfma_f32_16x16x32_bf16 v[72:75], v[64:67], v[182:185], v[72:75]
	v_mfma_f32_16x16x32_bf16 v[56:59], v[64:67], v[190:193], v[56:59]
	v_mfma_f32_16x16x32_bf16 v[60:63], v[48:51], v[190:193], v[60:63]
	v_mfma_f32_16x16x32_bf16 v[28:31], v[48:51], v[220:223], v[28:31]
	v_mfma_f32_16x16x32_bf16 v[24:27], v[64:67], v[220:223], v[24:27]
	v_mfma_f32_16x16x32_bf16 v[8:11], v[64:67], v[228:231], v[8:11]
	v_mfma_f32_16x16x32_bf16 v[12:15], v[48:51], v[228:231], v[12:15]
	v_mfma_f32_16x16x32_bf16 v[76:79], v[52:55], v[186:189], v[76:79]
	v_mfma_f32_16x16x32_bf16 v[72:75], v[68:71], v[186:189], v[72:75]
	v_mfma_f32_16x16x32_bf16 v[56:59], v[68:71], v[216:219], v[56:59]
	v_mfma_f32_16x16x32_bf16 v[60:63], v[52:55], v[216:219], v[60:63]
	v_mfma_f32_16x16x32_bf16 v[28:31], v[52:55], v[224:227], v[28:31]
	v_mfma_f32_16x16x32_bf16 v[24:27], v[68:71], v[224:227], v[24:27]
	v_mfma_f32_16x16x32_bf16 v[8:11], v[68:71], v[232:235], v[8:11]
	v_mfma_f32_16x16x32_bf16 v[12:15], v[52:55], v[232:235], v[12:15]
	v_mfma_f32_16x16x32_bf16 v[32:35], v[90:93], v[182:185], v[32:35]
	v_mfma_f32_16x16x32_bf16 v[68:71], v[94:97], v[186:189], v[32:35]
	v_mfma_f32_16x16x32_bf16 v[32:35], v[98:101], v[182:185], v[36:39]
	v_mfma_f32_16x16x32_bf16 v[64:67], v[102:105], v[186:189], v[32:35]
	v_mfma_f32_16x16x32_bf16 v[32:35], v[90:93], v[190:193], v[40:43]
	v_mfma_f32_16x16x32_bf16 v[52:55], v[94:97], v[216:219], v[32:35]
	v_mfma_f32_16x16x32_bf16 v[32:35], v[98:101], v[190:193], v[44:47]
	v_mfma_f32_16x16x32_bf16 v[20:23], v[90:93], v[220:223], v[20:23]
	v_mfma_f32_16x16x32_bf16 v[16:19], v[98:101], v[220:223], v[16:19]
	v_mfma_f32_16x16x32_bf16 v[4:7], v[90:93], v[228:231], v[4:7]
	v_mfma_f32_16x16x32_bf16 v[0:3], v[98:101], v[228:231], v[0:3]
	v_mfma_f32_16x16x32_bf16 v[48:51], v[102:105], v[216:219], v[32:35]
	v_mfma_f32_16x16x32_bf16 v[20:23], v[94:97], v[224:227], v[20:23]
	v_mfma_f32_16x16x32_bf16 v[16:19], v[102:105], v[224:227], v[16:19]
	v_mfma_f32_16x16x32_bf16 v[0:3], v[102:105], v[232:235], v[0:3]
	v_mfma_f32_16x16x32_bf16 v[4:7], v[94:97], v[232:235], v[4:7]
	s_setprio 0
	s_barrier
	s_add_i32 s13, s13, 2
	s_add_u32 s40, s40, 0x100
	s_addc_u32 s41, s41, 0
	s_add_u32 s11, s11, 0x100
	s_addc_u32 s12, s12, 0
	s_cmp_gt_u32 s13, 13
	s_cbranch_scc0 .LBB0_316

; #define PG8_STAGE(bufoff, gbase, voff) do { _Pragma("unroll") for (int _i = 0; _i < 2; ++_i) \
;         __builtin_amdgcn_global_load_lds((const unsigned*)((const char*)(gbase) + (voff)[_i]), (PG8_LAS unsigned*)(lds + (bufoff) + ldsw + _i * 8192), 16, 0, 0); } while (0)
; #define PG8_LDA(dst, b, h) do { _Pragma("unroll") for (int m = 0; m < 4; ++m) _Pragma("unroll") for (int k = 0; k < 2; ++k) dst[m][k] = *(const PG8_LAS bf16x8*)(lds + PG8_SA(b, h) + aoff + m * 2048 + k * 1024); } while (0)
; #define PG8_LDB(dst, b, h) do { _Pragma("unroll") for (int n = 0; n < 2; ++n) _Pragma("unroll") for (int k = 0; k < 2; ++k) dst[n][k] = *(const PG8_LAS bf16x8*)(lds + PG8_SB(b, h) + boff + n * 2048 + k * 1024); } while (0)
; #define PG8_WAIT_V(n) asm volatile("s_waitcnt vmcnt(" #n ")" ::: "memory")
; #define PG8_WAIT_L(n) asm volatile("s_waitcnt lgkmcnt(" #n ")" ::: "memory")
; #define PG8_BAR __builtin_amdgcn_s_barrier()
; template <class Epi, class Sched, bool ALIGN_EPI = false, bool SP2 = false>
; __device__ __forceinline__ void gemm_phase(PG8_LAS unsigned char* lds, const Gemm g, const Sched& S, const Epi& E) {
;     ...
;         const bool has_next = S.next(ui + 1, nxt);
;         const char* nA = has_next ? (const char*)g.A + (size_t)nxt.pm * tstep + (size_t)nxt.kt0 * kstep : cA; const char* nB = has_next ? (const char*)g.Bt + (size_t)nxt.pn * tstep + (size_t)nxt.kt0 * kstep : cB;
;         const int nt = cur.nt;
;         for (int t = 0; t < nt; t += 2) {
;             const bool last = (t == nt - 2);
;             const char* a1 = cA + (size_t)(t + 1) * kstep;
;             const char* a2 = last ? nA : cA + (size_t)(t + 2) * kstep; const char* b2 = last ? nB : cB + (size_t)(t + 2) * kstep;
;             const char* a3 = a2 + kstep; const char* b3 = b2 + kstep;
;             if (last && has_next) S.a_ready(nxt);
;             if constexpr (SP2) {
;             PG8_LDB(B0, 0, 0); PG8_LDB(B1, 0, 1); PG8_SCHED; PG8_LDA(At, 0, 0); PG8_STAGE(PG8_SA(1, 1), a1 + hstep, voffA);
;             PG8_WAIT_V(8); PG8_WAIT_L(0); PG8_BAR; PG8_MMA(0, 0, At, B0); PG8_MMA(0, 1, At, B1); PG8_BAR; PG8_SCHED;
;             PG8_LDA(At, 0, 1); PG8_STAGE(PG8_SB(0, 0), b2, voffB); PG8_STAGE(PG8_SB(0, 1), b2 + hstep, voffB); PG8_STAGE(PG8_SA(0, 0), a2, voffA);
;             PG8_WAIT_V(8); PG8_WAIT_L(0); PG8_BAR; PG8_MMA(1, 0, At, B0); PG8_MMA(1, 1, At, B1); PG8_BAR; PG8_SCHED;
.LBB0_646:
	s_add_i32 s24, s44, -2
	s_add_u32 s38, s38, 0x80
	s_addc_u32 s39, s39, 0
	s_add_u32 s41, s42, 0x100
	s_addc_u32 s45, s43, 0
	s_mov_b32 s42, 0
	s_waitcnt lgkmcnt(0)
	s_waitcnt vmcnt(0)
	s_add_i32 s71, s42, 2
	s_add_u32 s81, s38, 0x80
	s_addc_u32 s43, s39, 0
	s_add_i32 s94, 0, 0x10000
	s_cmp_eq_u32 s24, s42
	s_cselect_b32 s43, s27, s43
	s_cselect_b32 s42, s26, s81
	s_cselect_b32 s93, s91, s45
	s_cselect_b32 s92, s90, s41
	s_add_i32 s81, 0, 0x14000
	v_add_u32_e32 v142, s94, v213
	v_add_u32_e32 v151, s81, v213
	ds_read_b128 v[130:133], v142
	ds_read_b128 v[134:137], v142 offset:1024
	ds_read_b128 v[138:141], v142 offset:2048
	ds_read_b128 v[142:145], v142 offset:3072
	ds_read_b128 v[158:161], v151
	ds_read_b128 v[174:177], v151 offset:1024
	ds_read_b128 v[178:181], v151 offset:2048
	ds_read_b128 v[182:185], v151 offset:3072
	v_lshl_add_u64 v[194:195], s[38:39], 0, v[154:155]
	s_add_i32 m0, s17, 0xc000
	ds_read_b128 v[186:189], v214
	ds_read_b128 v[190:193], v214 offset:1024
	ds_read_b128 v[216:219], v214 offset:2048
	ds_read_b128 v[220:223], v214 offset:3072
	ds_read_b128 v[224:227], v214 offset:4096
	ds_read_b128 v[228:231], v214 offset:5120
	ds_read_b128 v[232:235], v214 offset:6144
	ds_read_b128 v[236:239], v214 offset:7168
	global_load_lds_dwordx4 v[194:195], off
	v_lshl_add_u64 v[194:195], s[38:39], 0, v[156:157]
	s_add_i32 m0, s17, 0xe000
	s_nop 0
	global_load_lds_dwordx4 v[194:195], off
	s_waitcnt vmcnt(8)
	s_waitcnt lgkmcnt(0)
	s_barrier
	s_setprio 1
	s_waitcnt lgkmcnt(0)
	v_mfma_f32_16x16x32_bf16 v[126:129], v[130:133], v[186:189], 0
	v_mfma_f32_16x16x32_bf16 v[122:125], v[138:141], v[186:189], 0
	v_mfma_f32_16x16x32_bf16 v[106:109], v[138:141], v[216:219], 0
	v_mfma_f32_16x16x32_bf16 v[110:113], v[130:133], v[216:219], 0
	v_mfma_f32_16x16x32_bf16 v[94:97], v[130:133], v[224:227], 0
	v_mfma_f32_16x16x32_bf16 v[90:93], v[138:141], v[224:227], 0
	v_mfma_f32_16x16x32_bf16 v[72:75], v[138:141], v[232:235], 0
	v_mfma_f32_16x16x32_bf16 v[76:79], v[130:133], v[232:235], 0
	v_mfma_f32_16x16x32_bf16 v[126:129], v[134:137], v[190:193], v[126:129]
	v_mfma_f32_16x16x32_bf16 v[122:125], v[142:145], v[190:193], v[122:125]
	v_mfma_f32_16x16x32_bf16 v[106:109], v[142:145], v[220:223], v[106:109]
	v_mfma_f32_16x16x32_bf16 v[110:113], v[134:137], v[220:223], v[110:113]
	v_mfma_f32_16x16x32_bf16 v[94:97], v[134:137], v[228:231], v[94:97]
	v_mfma_f32_16x16x32_bf16 v[90:93], v[142:145], v[228:231], v[90:93]
	v_mfma_f32_16x16x32_bf16 v[72:75], v[142:145], v[236:239], v[72:75]
	v_mfma_f32_16x16x32_bf16 v[76:79], v[134:137], v[236:239], v[76:79]
	v_mfma_f32_16x16x32_bf16 v[118:121], v[158:161], v[186:189], 0
	v_mfma_f32_16x16x32_bf16 v[114:117], v[178:181], v[186:189], 0
	v_mfma_f32_16x16x32_bf16 v[98:101], v[178:181], v[216:219], 0
	v_mfma_f32_16x16x32_bf16 v[102:105], v[158:161], v[216:219], 0
	v_mfma_f32_16x16x32_bf16 v[86:89], v[158:161], v[224:227], 0
	v_mfma_f32_16x16x32_bf16 v[82:85], v[178:181], v[224:227], 0
	v_mfma_f32_16x16x32_bf16 v[64:67], v[178:181], v[232:235], 0
	v_mfma_f32_16x16x32_bf16 v[68:71], v[158:161], v[232:235], 0
	v_mfma_f32_16x16x32_bf16 v[118:121], v[174:177], v[190:193], v[118:121]
	v_mfma_f32_16x16x32_bf16 v[114:117], v[182:185], v[190:193], v[114:117]
	v_mfma_f32_16x16x32_bf16 v[98:101], v[182:185], v[220:223], v[98:101]
	v_mfma_f32_16x16x32_bf16 v[102:105], v[174:177], v[220:223], v[102:105]
	v_mfma_f32_16x16x32_bf16 v[86:89], v[174:177], v[228:231], v[86:89]
	v_mfma_f32_16x16x32_bf16 v[82:85], v[182:185], v[228:231], v[82:85]
	v_mfma_f32_16x16x32_bf16 v[64:67], v[182:185], v[236:239], v[64:67]
	v_mfma_f32_16x16x32_bf16 v[68:71], v[174:177], v[236:239], v[68:71]
	s_setprio 0
	s_barrier
	s_add_i32 s94, s94, s16
	v_lshl_add_u64 v[194:195], s[92:93], 0, v[146:147]
	s_mov_b32 m0, s94
	s_nop 0
	global_load_lds_dwordx4 v[194:195], off
	s_add_i32 m0, s94, 0x2000
	v_lshl_add_u64 v[240:241], s[92:93], 0, v[148:149]
	s_add_u32 s92, s92, s30
	s_addc_u32 s93, s93, 0
	s_add_i32 s81, s81, s16
	global_load_lds_dwordx4 v[240:241], off
	v_lshl_add_u64 v[242:243], s[92:93], 0, v[146:147]
	s_mov_b32 m0, s81
	v_lshl_add_u64 v[244:245], s[92:93], 0, v[148:149]
	global_load_lds_dwordx4 v[242:243], off
	s_add_i32 m0, s81, 0x2000
	v_lshl_add_u64 v[246:247], s[42:43], 0, v[146:147]
	global_load_lds_dwordx4 v[244:245], off
	s_mov_b32 m0, s17
	v_lshl_add_u64 v[248:249], s[42:43], 0, v[148:149]
	global_load_lds_dwordx4 v[246:247], off
	s_mov_b32 m0, s18
	s_nop 0
	global_load_lds_dwordx4 v[248:249], off
	ds_read_b128 v[186:189], v214 offset:16384
	ds_read_b128 v[190:193], v214 offset:17408
	ds_read_b128 v[216:219], v214 offset:18432
	ds_read_b128 v[220:223], v214 offset:19456
	ds_read_b128 v[224:227], v214 offset:20480
	ds_read_b128 v[228:231], v214 offset:21504
	ds_read_b128 v[232:235], v214 offset:22528
	ds_read_b128 v[236:239], v214 offset:23552
	s_waitcnt vmcnt(8)
	s_waitcnt lgkmcnt(0)
	s_barrier
; #define PG8_STAGE(bufoff, gbase, voff) do { _Pragma("unroll") for (int _i = 0; _i < 2; ++_i) \
;         __builtin_amdgcn_global_load_lds((const unsigned*)((const char*)(gbase) + (voff)[_i]), (PG8_LAS unsigned*)(lds + (bufoff) + ldsw + _i * 8192), 16, 0, 0); } while (0)
; #define PG8_LDA(dst, b, h) do { _Pragma("unroll") for (int m = 0; m < 4; ++m) _Pragma("unroll") for (int k = 0; k < 2; ++k) dst[m][k] = *(const PG8_LAS bf16x8*)(lds + PG8_SA(b, h) + aoff + m * 2048 + k * 1024); } while (0)
; #define PG8_LDB(dst, b, h) do { _Pragma("unroll") for (int n = 0; n < 2; ++n) _Pragma("unroll") for (int k = 0; k < 2; ++k) dst[n][k] = *(const PG8_LAS bf16x8*)(lds + PG8_SB(b, h) + boff + n * 2048 + k * 1024); } while (0)
; #define PG8_MMA(ai, bj, At, Bt) do { __builtin_amdgcn_s_setprio(1); _Pragma("unroll") for (int m = 0; m < 4; ++m) _Pragma("unroll") for (int n = 0; n < 2; ++n) _Pragma("unroll") for (int k = 0; k < 2; ++k) \
;         acc[ai][bj][m][n] = __builtin_amdgcn_mfma_f32_16x16x32_bf16(Bt[n][k], At[m][k], acc[ai][bj][m][n], 0, 0, 0); __builtin_amdgcn_s_setprio(0); } while (0)
; #define PG8_WAIT_V(n) asm volatile("s_waitcnt vmcnt(" #n ")" ::: "memory")
; #define PG8_WAIT_L(n) asm volatile("s_waitcnt lgkmcnt(" #n ")" ::: "memory")
; #define PG8_BAR __builtin_amdgcn_s_barrier()
; #define PG8_SCHED __builtin_amdgcn_sched_barrier(0)
; template <class Epi, class Sched, bool ALIGN_EPI = false, bool SP2 = false>
; __device__ __forceinline__ void gemm_phase(PG8_LAS unsigned char* lds, const Gemm g, const Sched& S, const Epi& E) {
;     ...
;             PG8_WAIT_V(8); PG8_WAIT_L(0); PG8_BAR; PG8_MMA(1, 0, At, B0); PG8_MMA(1, 1, At, B1); PG8_BAR; PG8_SCHED;
;             PG8_LDB(B0, 1, 0); PG8_LDB(B1, 1, 1); PG8_SCHED; PG8_LDA(At, 1, 0); PG8_STAGE(PG8_SA(0, 1), a2 + hstep, voffA);
;             PG8_WAIT_V(8); PG8_WAIT_L(0); PG8_BAR; PG8_MMA(0, 0, At, B0); PG8_MMA(0, 1, At, B1); PG8_BAR; PG8_SCHED;
	s_setprio 1
	s_waitcnt lgkmcnt(0)
	v_mfma_f32_16x16x32_bf16 v[60:63], v[130:133], v[186:189], 0
	v_mfma_f32_16x16x32_bf16 v[56:59], v[138:141], v[186:189], 0
	v_mfma_f32_16x16x32_bf16 v[40:43], v[138:141], v[216:219], 0
	v_mfma_f32_16x16x32_bf16 v[44:47], v[130:133], v[216:219], 0
	v_mfma_f32_16x16x32_bf16 v[28:31], v[130:133], v[224:227], 0
	v_mfma_f32_16x16x32_bf16 v[24:27], v[138:141], v[224:227], 0
	v_mfma_f32_16x16x32_bf16 v[8:11], v[138:141], v[232:235], 0
	v_mfma_f32_16x16x32_bf16 v[12:15], v[130:133], v[232:235], 0
	v_mfma_f32_16x16x32_bf16 v[60:63], v[134:137], v[190:193], v[60:63]
	v_mfma_f32_16x16x32_bf16 v[56:59], v[142:145], v[190:193], v[56:59]
	v_mfma_f32_16x16x32_bf16 v[40:43], v[142:145], v[220:223], v[40:43]
	v_mfma_f32_16x16x32_bf16 v[44:47], v[134:137], v[220:223], v[44:47]
	v_mfma_f32_16x16x32_bf16 v[28:31], v[134:137], v[228:231], v[28:31]
	v_mfma_f32_16x16x32_bf16 v[24:27], v[142:145], v[228:231], v[24:27]
	v_mfma_f32_16x16x32_bf16 v[8:11], v[142:145], v[236:239], v[8:11]
	v_mfma_f32_16x16x32_bf16 v[12:15], v[134:137], v[236:239], v[12:15]
	v_mfma_f32_16x16x32_bf16 v[52:55], v[158:161], v[186:189], 0
	v_mfma_f32_16x16x32_bf16 v[48:51], v[178:181], v[186:189], 0
	v_mfma_f32_16x16x32_bf16 v[32:35], v[178:181], v[216:219], 0
	v_mfma_f32_16x16x32_bf16 v[36:39], v[158:161], v[216:219], 0
	v_mfma_f32_16x16x32_bf16 v[20:23], v[158:161], v[224:227], 0
	v_mfma_f32_16x16x32_bf16 v[16:19], v[178:181], v[224:227], 0
	v_mfma_f32_16x16x32_bf16 v[0:3], v[178:181], v[232:235], 0
	v_mfma_f32_16x16x32_bf16 v[4:7], v[158:161], v[232:235], 0
	v_mfma_f32_16x16x32_bf16 v[52:55], v[174:177], v[190:193], v[52:55]
	v_mfma_f32_16x16x32_bf16 v[48:51], v[182:185], v[190:193], v[48:51]
	v_mfma_f32_16x16x32_bf16 v[32:35], v[182:185], v[220:223], v[32:35]
	v_mfma_f32_16x16x32_bf16 v[36:39], v[174:177], v[220:223], v[36:39]
	v_mfma_f32_16x16x32_bf16 v[20:23], v[174:177], v[228:231], v[20:23]
	v_mfma_f32_16x16x32_bf16 v[16:19], v[182:185], v[228:231], v[16:19]
	v_mfma_f32_16x16x32_bf16 v[0:3], v[182:185], v[236:239], v[0:3]
	v_mfma_f32_16x16x32_bf16 v[4:7], v[174:177], v[236:239], v[4:7]
	s_setprio 0
	s_barrier
	s_add_i32 s81, 0, 0x18000
	s_add_i32 s92, 0, 0x1c000
	v_add_u32_e32 v142, s81, v213
	v_add_u32_e32 v151, s92, v213
	s_add_u32 s42, s42, s30
	s_addc_u32 s43, s43, 0
	s_mov_b32 m0, s19
	v_lshl_add_u64 v[250:251], s[42:43], 0, v[146:147]
	global_load_lds_dwordx4 v[250:251], off
	v_lshl_add_u64 v[250:251], s[42:43], 0, v[148:149]
	s_mov_b32 m0, s20
	s_nop 0
	global_load_lds_dwordx4 v[250:251], off
	ds_read_b128 v[130:133], v142
	ds_read_b128 v[134:137], v142 offset:1024
	ds_read_b128 v[138:141], v142 offset:2048
	ds_read_b128 v[142:145], v142 offset:3072
	ds_read_b128 v[158:161], v151
	ds_read_b128 v[174:177], v151 offset:1024
	ds_read_b128 v[178:181], v151 offset:2048
	ds_read_b128 v[182:185], v151 offset:3072
	ds_read_b128 v[186:189], v214 offset:32768
	ds_read_b128 v[190:193], v214 offset:33792
	ds_read_b128 v[216:219], v214 offset:34816
	ds_read_b128 v[220:223], v214 offset:35840
	ds_read_b128 v[224:227], v214 offset:36864
	ds_read_b128 v[228:231], v214 offset:37888
	ds_read_b128 v[232:235], v214 offset:38912
	ds_read_b128 v[236:239], v214 offset:39936
	s_waitcnt vmcnt(8)
	s_waitcnt lgkmcnt(0)
	s_barrier
	s_setprio 1
	s_waitcnt lgkmcnt(0)
	v_mfma_f32_16x16x32_bf16 v[126:129], v[130:133], v[186:189], v[126:129]
	v_mfma_f32_16x16x32_bf16 v[122:125], v[138:141], v[186:189], v[122:125]
	v_mfma_f32_16x16x32_bf16 v[106:109], v[138:141], v[216:219], v[106:109]
	v_mfma_f32_16x16x32_bf16 v[110:113], v[130:133], v[216:219], v[110:113]
	v_mfma_f32_16x16x32_bf16 v[94:97], v[130:133], v[224:227], v[94:97]
	v_mfma_f32_16x16x32_bf16 v[90:93], v[138:141], v[224:227], v[90:93]
	v_mfma_f32_16x16x32_bf16 v[72:75], v[138:141], v[232:235], v[72:75]
	v_mfma_f32_16x16x32_bf16 v[76:79], v[130:133], v[232:235], v[76:79]
	v_mfma_f32_16x16x32_bf16 v[126:129], v[134:137], v[190:193], v[126:129]
	v_mfma_f32_16x16x32_bf16 v[122:125], v[142:145], v[190:193], v[122:125]
	v_mfma_f32_16x16x32_bf16 v[106:109], v[142:145], v[220:223], v[106:109]
	v_mfma_f32_16x16x32_bf16 v[110:113], v[134:137], v[220:223], v[110:113]
	v_mfma_f32_16x16x32_bf16 v[94:97], v[134:137], v[228:231], v[94:97]
	v_mfma_f32_16x16x32_bf16 v[90:93], v[142:145], v[228:231], v[90:93]
	v_mfma_f32_16x16x32_bf16 v[72:75], v[142:145], v[236:239], v[72:75]
	v_mfma_f32_16x16x32_bf16 v[76:79], v[134:137], v[236:239], v[76:79]
	v_mfma_f32_16x16x32_bf16 v[118:121], v[158:161], v[186:189], v[118:121]
	v_mfma_f32_16x16x32_bf16 v[114:117], v[178:181], v[186:189], v[114:117]
	v_mfma_f32_16x16x32_bf16 v[98:101], v[178:181], v[216:219], v[98:101]
	v_mfma_f32_16x16x32_bf16 v[102:105], v[158:161], v[216:219], v[102:105]
	v_mfma_f32_16x16x32_bf16 v[86:89], v[158:161], v[224:227], v[86:89]
	v_mfma_f32_16x16x32_bf16 v[82:85], v[178:181], v[224:227], v[82:85]
	v_mfma_f32_16x16x32_bf16 v[64:67], v[178:181], v[232:235], v[64:67]
	v_mfma_f32_16x16x32_bf16 v[68:71], v[158:161], v[232:235], v[68:71]
	v_mfma_f32_16x16x32_bf16 v[118:121], v[174:177], v[190:193], v[118:121]
	v_mfma_f32_16x16x32_bf16 v[114:117], v[182:185], v[190:193], v[114:117]
	v_mfma_f32_16x16x32_bf16 v[98:101], v[182:185], v[220:223], v[98:101]
	v_mfma_f32_16x16x32_bf16 v[102:105], v[174:177], v[220:223], v[102:105]
	v_mfma_f32_16x16x32_bf16 v[86:89], v[174:177], v[228:231], v[86:89]
	v_mfma_f32_16x16x32_bf16 v[82:85], v[182:185], v[228:231], v[82:85]
	v_mfma_f32_16x16x32_bf16 v[64:67], v[182:185], v[236:239], v[64:67]
	v_mfma_f32_16x16x32_bf16 v[68:71], v[174:177], v[236:239], v[68:71]
	s_setprio 0
	s_barrier
; #define PG8_STAGE(bufoff, gbase, voff) do { _Pragma("unroll") for (int _i = 0; _i < 2; ++_i) \
;         __builtin_amdgcn_global_load_lds((const unsigned*)((const char*)(gbase) + (voff)[_i]), (PG8_LAS unsigned*)(lds + (bufoff) + ldsw + _i * 8192), 16, 0, 0); } while (0)
; #define PG8_LDA(dst, b, h) do { _Pragma("unroll") for (int m = 0; m < 4; ++m) _Pragma("unroll") for (int k = 0; k < 2; ++k) dst[m][k] = *(const PG8_LAS bf16x8*)(lds + PG8_SA(b, h) + aoff + m * 2048 + k * 1024); } while (0)
; #define PG8_LDB(dst, b, h) do { _Pragma("unroll") for (int n = 0; n < 2; ++n) _Pragma("unroll") for (int k = 0; k < 2; ++k) dst[n][k] = *(const PG8_LAS bf16x8*)(lds + PG8_SB(b, h) + boff + n * 2048 + k * 1024); } while (0)
; #define PG8_BAR __builtin_amdgcn_s_barrier()
; template <class Epi, class Sched, bool ALIGN_EPI = false, bool SP2 = false>
; __device__ __forceinline__ void gemm_phase(PG8_LAS unsigned char* lds, const Gemm g, const Sched& S, const Epi& E) {
;     ...
;             const bool last = (t == nt - 2);
;             const char* a1 = cA + (size_t)(t + 1) * kstep;
;             const char* a2 = last ? nA : cA + (size_t)(t + 2) * kstep; const char* b2 = last ? nB : cB + (size_t)(t + 2) * kstep;
;             const char* a3 = a2 + kstep; const char* b3 = b2 + kstep;
;             if (last && has_next) S.a_ready(nxt);
;             if constexpr (SP2) {
;             PG8_LDB(B0, 0, 0); PG8_LDB(B1, 0, 1); PG8_SCHED; PG8_LDA(At, 0, 0); PG8_STAGE(PG8_SA(1, 1), a1 + hstep, voffA);
;             PG8_WAIT_V(8); PG8_WAIT_L(0); PG8_BAR; PG8_MMA(0, 0, At, B0); PG8_MMA(0, 1, At, B1); PG8_BAR; PG8_SCHED;
;             PG8_LDA(At, 0, 1); PG8_STAGE(PG8_SB(0, 0), b2, voffB); PG8_STAGE(PG8_SB(0, 1), b2 + hstep, voffB); PG8_STAGE(PG8_SA(0, 0), a2, voffA);
;             PG8_WAIT_V(8); PG8_WAIT_L(0); PG8_BAR; PG8_MMA(1, 0, At, B0); PG8_MMA(1, 1, At, B1); PG8_BAR; PG8_SCHED;
;             PG8_LDB(B0, 1, 0); PG8_LDB(B1, 1, 1); PG8_SCHED; PG8_LDA(At, 1, 0); PG8_STAGE(PG8_SA(0, 1), a2 + hstep, voffA);
;             PG8_WAIT_V(8); PG8_WAIT_L(0); PG8_BAR; PG8_MMA(0, 0, At, B0); PG8_MMA(0, 1, At, B1); PG8_BAR; PG8_SCHED;
;             PG8_LDA(At, 1, 1); PG8_STAGE(PG8_SB(1, 0), b3, voffB); PG8_STAGE(PG8_SB(1, 1), b3 + hstep, voffB); PG8_STAGE(PG8_SA(1, 0), a3, voffA);
;             PG8_WAIT_V(8); PG8_WAIT_L(0); PG8_BAR; PG8_MMA(1, 0, At, B0); PG8_MMA(1, 1, At, B1); PG8_BAR; PG8_SCHED;
	s_add_i32 s42, s81, s16
	v_lshl_add_u64 v[194:195], v[194:195], 0, s[0:1]
	s_mov_b32 m0, s42
	s_nop 0
	global_load_lds_dwordx4 v[194:195], off
	v_lshl_add_u64 v[194:195], v[240:241], 0, s[0:1]
	s_add_i32 m0, s42, 0x2000
	s_add_i32 s42, s92, s16
	global_load_lds_dwordx4 v[194:195], off
	v_lshl_add_u64 v[194:195], v[242:243], 0, s[0:1]
	s_mov_b32 m0, s42
	s_nop 0
	global_load_lds_dwordx4 v[194:195], off
	v_lshl_add_u64 v[194:195], v[244:245], 0, s[0:1]
	s_add_i32 m0, s42, 0x2000
	s_nop 0
	global_load_lds_dwordx4 v[194:195], off
	v_lshl_add_u64 v[194:195], v[246:247], 0, s[0:1]
	s_mov_b32 m0, s8
	s_nop 0
	global_load_lds_dwordx4 v[194:195], off
	v_lshl_add_u64 v[194:195], v[248:249], 0, s[0:1]
	s_mov_b32 m0, s9
	s_nop 0
	global_load_lds_dwordx4 v[194:195], off
	ds_read_b128 v[186:189], v214 offset:49152
	ds_read_b128 v[190:193], v214 offset:50176
	ds_read_b128 v[216:219], v214 offset:51200
	ds_read_b128 v[220:223], v214 offset:52224
	ds_read_b128 v[224:227], v214 offset:53248
	ds_read_b128 v[228:231], v214 offset:54272
	ds_read_b128 v[232:235], v214 offset:55296
	ds_read_b128 v[236:239], v214 offset:56320
	s_waitcnt vmcnt(8)
	s_waitcnt lgkmcnt(0)
	s_barrier
	s_setprio 1
	s_waitcnt lgkmcnt(0)
	v_mfma_f32_16x16x32_bf16 v[60:63], v[130:133], v[186:189], v[60:63]
	v_mfma_f32_16x16x32_bf16 v[56:59], v[138:141], v[186:189], v[56:59]
	v_mfma_f32_16x16x32_bf16 v[40:43], v[138:141], v[216:219], v[40:43]
	v_mfma_f32_16x16x32_bf16 v[44:47], v[130:133], v[216:219], v[44:47]
	v_mfma_f32_16x16x32_bf16 v[28:31], v[130:133], v[224:227], v[28:31]
	v_mfma_f32_16x16x32_bf16 v[24:27], v[138:141], v[224:227], v[24:27]
	v_mfma_f32_16x16x32_bf16 v[8:11], v[138:141], v[232:235], v[8:11]
	v_mfma_f32_16x16x32_bf16 v[12:15], v[130:133], v[232:235], v[12:15]
	v_mfma_f32_16x16x32_bf16 v[60:63], v[134:137], v[190:193], v[60:63]
	v_mfma_f32_16x16x32_bf16 v[56:59], v[142:145], v[190:193], v[56:59]
	v_mfma_f32_16x16x32_bf16 v[40:43], v[142:145], v[220:223], v[40:43]
	v_mfma_f32_16x16x32_bf16 v[44:47], v[134:137], v[220:223], v[44:47]
	v_mfma_f32_16x16x32_bf16 v[28:31], v[134:137], v[228:231], v[28:31]
	v_mfma_f32_16x16x32_bf16 v[24:27], v[142:145], v[228:231], v[24:27]
	v_mfma_f32_16x16x32_bf16 v[8:11], v[142:145], v[236:239], v[8:11]
	v_mfma_f32_16x16x32_bf16 v[12:15], v[134:137], v[236:239], v[12:15]
	v_mfma_f32_16x16x32_bf16 v[52:55], v[158:161], v[186:189], v[52:55]
	v_mfma_f32_16x16x32_bf16 v[48:51], v[178:181], v[186:189], v[48:51]
	v_mfma_f32_16x16x32_bf16 v[32:35], v[178:181], v[216:219], v[32:35]
	v_mfma_f32_16x16x32_bf16 v[36:39], v[158:161], v[216:219], v[36:39]
	v_mfma_f32_16x16x32_bf16 v[20:23], v[158:161], v[224:227], v[20:23]
	v_mfma_f32_16x16x32_bf16 v[16:19], v[178:181], v[224:227], v[16:19]
	v_mfma_f32_16x16x32_bf16 v[0:3], v[178:181], v[232:235], v[0:3]
	v_mfma_f32_16x16x32_bf16 v[4:7], v[158:161], v[232:235], v[4:7]
	v_mfma_f32_16x16x32_bf16 v[52:55], v[174:177], v[190:193], v[52:55]
	v_mfma_f32_16x16x32_bf16 v[48:51], v[182:185], v[190:193], v[48:51]
	v_mfma_f32_16x16x32_bf16 v[32:35], v[182:185], v[220:223], v[32:35]
	v_mfma_f32_16x16x32_bf16 v[36:39], v[174:177], v[220:223], v[36:39]
	v_mfma_f32_16x16x32_bf16 v[20:23], v[174:177], v[228:231], v[20:23]
	v_mfma_f32_16x16x32_bf16 v[16:19], v[182:185], v[228:231], v[16:19]
	v_mfma_f32_16x16x32_bf16 v[0:3], v[182:185], v[236:239], v[0:3]
	v_mfma_f32_16x16x32_bf16 v[4:7], v[174:177], v[236:239], v[4:7]
	s_setprio 0
	s_barrier
	s_add_u32 s38, s38, 0x100
	s_addc_u32 s39, s39, 0
	s_add_u32 s41, s41, 0x100
	s_addc_u32 s45, s45, 0
	s_cmp_ge_u32 s71, s44
	s_mov_b32 s42, s71
	s_cbranch_scc1 .Lpeel_done_0
.LBB0_647:
	s_add_i32 s71, s42, 2
	s_add_u32 s81, s38, 0x80
	s_addc_u32 s43, s39, 0
	s_add_i32 s94, 0, 0x10000
	s_cmp_eq_u32 s24, s42
	s_cselect_b32 s43, s27, s43
	s_cselect_b32 s42, s26, s81
	s_cselect_b32 s93, s91, s45
	s_cselect_b32 s92, s90, s41
	s_add_i32 s81, 0, 0x14000
	v_add_u32_e32 v142, s94, v213
	v_add_u32_e32 v151, s81, v213
	v_lshl_add_u64 v[194:195], s[38:39], 0, v[154:155]
	s_add_i32 m0, s17, 0xc000
	s_nop 0
	global_load_lds_dwordx4 v[194:195], off
	v_lshl_add_u64 v[194:195], s[38:39], 0, v[156:157]
	s_add_i32 m0, s17, 0xe000
	s_nop 0
	global_load_lds_dwordx4 v[194:195], off
	ds_read_b128 v[130:133], v142
	ds_read_b128 v[134:137], v142 offset:1024
	ds_read_b128 v[138:141], v142 offset:2048
	ds_read_b128 v[142:145], v142 offset:3072
	ds_read_b128 v[158:161], v151
	ds_read_b128 v[174:177], v151 offset:1024
	ds_read_b128 v[178:181], v151 offset:2048
	ds_read_b128 v[182:185], v151 offset:3072
	ds_read_b128 v[186:189], v214
	ds_read_b128 v[190:193], v214 offset:1024
	ds_read_b128 v[216:219], v214 offset:2048
	ds_read_b128 v[220:223], v214 offset:3072
	ds_read_b128 v[224:227], v214 offset:4096
	ds_read_b128 v[228:231], v214 offset:5120
	ds_read_b128 v[232:235], v214 offset:6144
	ds_read_b128 v[236:239], v214 offset:7168
	s_waitcnt vmcnt(8)
	s_waitcnt lgkmcnt(0)
	s_barrier
; #define PG8_STAGE(bufoff, gbase, voff) do { _Pragma("unroll") for (int _i = 0; _i < 2; ++_i) \
;         __builtin_amdgcn_global_load_lds((const unsigned*)((const char*)(gbase) + (voff)[_i]), (PG8_LAS unsigned*)(lds + (bufoff) + ldsw + _i * 8192), 16, 0, 0); } while (0)
; #define PG8_LDA(dst, b, h) do { _Pragma("unroll") for (int m = 0; m < 4; ++m) _Pragma("unroll") for (int k = 0; k < 2; ++k) dst[m][k] = *(const PG8_LAS bf16x8*)(lds + PG8_SA(b, h) + aoff + m * 2048 + k * 1024); } while (0)
; #define PG8_MMA(ai, bj, At, Bt) do { __builtin_amdgcn_s_setprio(1); _Pragma("unroll") for (int m = 0; m < 4; ++m) _Pragma("unroll") for (int n = 0; n < 2; ++n) _Pragma("unroll") for (int k = 0; k < 2; ++k) \
;         acc[ai][bj][m][n] = __builtin_amdgcn_mfma_f32_16x16x32_bf16(Bt[n][k], At[m][k], acc[ai][bj][m][n], 0, 0, 0); __builtin_amdgcn_s_setprio(0); } while (0)
; #define PG8_WAIT_V(n) asm volatile("s_waitcnt vmcnt(" #n ")" ::: "memory")
; #define PG8_WAIT_L(n) asm volatile("s_waitcnt lgkmcnt(" #n ")" ::: "memory")
; #define PG8_BAR __builtin_amdgcn_s_barrier()
; #define PG8_SCHED __builtin_amdgcn_sched_barrier(0)
; template <class Epi, class Sched, bool ALIGN_EPI = false, bool SP2 = false>
; __device__ __forceinline__ void gemm_phase(PG8_LAS unsigned char* lds, const Gemm g, const Sched& S, const Epi& E) {
;     ...
;             PG8_WAIT_V(8); PG8_WAIT_L(0); PG8_BAR; PG8_MMA(0, 0, At, B0); PG8_MMA(0, 1, At, B1); PG8_BAR; PG8_SCHED;
;             PG8_LDA(At, 0, 1); PG8_STAGE(PG8_SB(0, 0), b2, voffB); PG8_STAGE(PG8_SB(0, 1), b2 + hstep, voffB); PG8_STAGE(PG8_SA(0, 0), a2, voffA);
;             PG8_WAIT_V(8); PG8_WAIT_L(0); PG8_BAR; PG8_MMA(1, 0, At, B0); PG8_MMA(1, 1, At, B1); PG8_BAR; PG8_SCHED;
	s_setprio 1
	s_waitcnt lgkmcnt(0)
	v_mfma_f32_16x16x32_bf16 v[126:129], v[130:133], v[186:189], v[126:129]
	v_mfma_f32_16x16x32_bf16 v[122:125], v[138:141], v[186:189], v[122:125]
	v_mfma_f32_16x16x32_bf16 v[106:109], v[138:141], v[216:219], v[106:109]
	v_mfma_f32_16x16x32_bf16 v[110:113], v[130:133], v[216:219], v[110:113]
	v_mfma_f32_16x16x32_bf16 v[94:97], v[130:133], v[224:227], v[94:97]
	v_mfma_f32_16x16x32_bf16 v[90:93], v[138:141], v[224:227], v[90:93]
	v_mfma_f32_16x16x32_bf16 v[72:75], v[138:141], v[232:235], v[72:75]
	v_mfma_f32_16x16x32_bf16 v[76:79], v[130:133], v[232:235], v[76:79]
	v_mfma_f32_16x16x32_bf16 v[126:129], v[134:137], v[190:193], v[126:129]
	v_mfma_f32_16x16x32_bf16 v[122:125], v[142:145], v[190:193], v[122:125]
	v_mfma_f32_16x16x32_bf16 v[106:109], v[142:145], v[220:223], v[106:109]
	v_mfma_f32_16x16x32_bf16 v[110:113], v[134:137], v[220:223], v[110:113]
	v_mfma_f32_16x16x32_bf16 v[94:97], v[134:137], v[228:231], v[94:97]
	v_mfma_f32_16x16x32_bf16 v[90:93], v[142:145], v[228:231], v[90:93]
	v_mfma_f32_16x16x32_bf16 v[72:75], v[142:145], v[236:239], v[72:75]
	v_mfma_f32_16x16x32_bf16 v[76:79], v[134:137], v[236:239], v[76:79]
	v_mfma_f32_16x16x32_bf16 v[118:121], v[158:161], v[186:189], v[118:121]
	v_mfma_f32_16x16x32_bf16 v[114:117], v[178:181], v[186:189], v[114:117]
	v_mfma_f32_16x16x32_bf16 v[98:101], v[178:181], v[216:219], v[98:101]
	v_mfma_f32_16x16x32_bf16 v[102:105], v[158:161], v[216:219], v[102:105]
	v_mfma_f32_16x16x32_bf16 v[86:89], v[158:161], v[224:227], v[86:89]
	v_mfma_f32_16x16x32_bf16 v[82:85], v[178:181], v[224:227], v[82:85]
	v_mfma_f32_16x16x32_bf16 v[64:67], v[178:181], v[232:235], v[64:67]
	v_mfma_f32_16x16x32_bf16 v[68:71], v[158:161], v[232:235], v[68:71]
	v_mfma_f32_16x16x32_bf16 v[118:121], v[174:177], v[190:193], v[118:121]
	v_mfma_f32_16x16x32_bf16 v[114:117], v[182:185], v[190:193], v[114:117]
	v_mfma_f32_16x16x32_bf16 v[98:101], v[182:185], v[220:223], v[98:101]
	v_mfma_f32_16x16x32_bf16 v[102:105], v[174:177], v[220:223], v[102:105]
	v_mfma_f32_16x16x32_bf16 v[86:89], v[174:177], v[228:231], v[86:89]
	v_mfma_f32_16x16x32_bf16 v[82:85], v[182:185], v[228:231], v[82:85]
	v_mfma_f32_16x16x32_bf16 v[64:67], v[182:185], v[236:239], v[64:67]
	v_mfma_f32_16x16x32_bf16 v[68:71], v[174:177], v[236:239], v[68:71]
	s_setprio 0
	s_barrier
	s_add_i32 s94, s94, s16
	v_lshl_add_u64 v[194:195], s[92:93], 0, v[146:147]
	s_mov_b32 m0, s94
	s_nop 0
	global_load_lds_dwordx4 v[194:195], off
	s_add_i32 m0, s94, 0x2000
	v_lshl_add_u64 v[240:241], s[92:93], 0, v[148:149]
	s_add_u32 s92, s92, s30
	s_addc_u32 s93, s93, 0
	s_add_i32 s81, s81, s16
	global_load_lds_dwordx4 v[240:241], off
	v_lshl_add_u64 v[242:243], s[92:93], 0, v[146:147]
	s_mov_b32 m0, s81
	v_lshl_add_u64 v[244:245], s[92:93], 0, v[148:149]
	global_load_lds_dwordx4 v[242:243], off
	s_add_i32 m0, s81, 0x2000
	v_lshl_add_u64 v[246:247], s[42:43], 0, v[146:147]
	global_load_lds_dwordx4 v[244:245], off
	s_mov_b32 m0, s17
	v_lshl_add_u64 v[248:249], s[42:43], 0, v[148:149]
	global_load_lds_dwordx4 v[246:247], off
	s_mov_b32 m0, s18
	s_nop 0
	global_load_lds_dwordx4 v[248:249], off
	ds_read_b128 v[186:189], v214 offset:16384
	ds_read_b128 v[190:193], v214 offset:17408
	ds_read_b128 v[216:219], v214 offset:18432
	ds_read_b128 v[220:223], v214 offset:19456
	ds_read_b128 v[224:227], v214 offset:20480
	ds_read_b128 v[228:231], v214 offset:21504
	ds_read_b128 v[232:235], v214 offset:22528
	ds_read_b128 v[236:239], v214 offset:23552
	s_waitcnt vmcnt(8)
	s_waitcnt lgkmcnt(0)
	s_barrier
	s_setprio 1
	s_waitcnt lgkmcnt(0)
	v_mfma_f32_16x16x32_bf16 v[60:63], v[130:133], v[186:189], v[60:63]
	v_mfma_f32_16x16x32_bf16 v[56:59], v[138:141], v[186:189], v[56:59]
	v_mfma_f32_16x16x32_bf16 v[40:43], v[138:141], v[216:219], v[40:43]
	v_mfma_f32_16x16x32_bf16 v[44:47], v[130:133], v[216:219], v[44:47]
	v_mfma_f32_16x16x32_bf16 v[28:31], v[130:133], v[224:227], v[28:31]
	v_mfma_f32_16x16x32_bf16 v[24:27], v[138:141], v[224:227], v[24:27]
	v_mfma_f32_16x16x32_bf16 v[8:11], v[138:141], v[232:235], v[8:11]
	v_mfma_f32_16x16x32_bf16 v[12:15], v[130:133], v[232:235], v[12:15]
	v_mfma_f32_16x16x32_bf16 v[60:63], v[134:137], v[190:193], v[60:63]
	v_mfma_f32_16x16x32_bf16 v[56:59], v[142:145], v[190:193], v[56:59]
	v_mfma_f32_16x16x32_bf16 v[40:43], v[142:145], v[220:223], v[40:43]
	v_mfma_f32_16x16x32_bf16 v[44:47], v[134:137], v[220:223], v[44:47]
	v_mfma_f32_16x16x32_bf16 v[28:31], v[134:137], v[228:231], v[28:31]
	v_mfma_f32_16x16x32_bf16 v[24:27], v[142:145], v[228:231], v[24:27]
	v_mfma_f32_16x16x32_bf16 v[8:11], v[142:145], v[236:239], v[8:11]
	v_mfma_f32_16x16x32_bf16 v[12:15], v[134:137], v[236:239], v[12:15]
	v_mfma_f32_16x16x32_bf16 v[52:55], v[158:161], v[186:189], v[52:55]
	v_mfma_f32_16x16x32_bf16 v[48:51], v[178:181], v[186:189], v[48:51]
	v_mfma_f32_16x16x32_bf16 v[32:35], v[178:181], v[216:219], v[32:35]
	v_mfma_f32_16x16x32_bf16 v[36:39], v[158:161], v[216:219], v[36:39]
	v_mfma_f32_16x16x32_bf16 v[20:23], v[158:161], v[224:227], v[20:23]
	v_mfma_f32_16x16x32_bf16 v[16:19], v[178:181], v[224:227], v[16:19]
	v_mfma_f32_16x16x32_bf16 v[0:3], v[178:181], v[232:235], v[0:3]
	v_mfma_f32_16x16x32_bf16 v[4:7], v[158:161], v[232:235], v[4:7]
	v_mfma_f32_16x16x32_bf16 v[52:55], v[174:177], v[190:193], v[52:55]
	v_mfma_f32_16x16x32_bf16 v[48:51], v[182:185], v[190:193], v[48:51]
	v_mfma_f32_16x16x32_bf16 v[32:35], v[182:185], v[220:223], v[32:35]
	v_mfma_f32_16x16x32_bf16 v[36:39], v[174:177], v[220:223], v[36:39]
	v_mfma_f32_16x16x32_bf16 v[20:23], v[174:177], v[228:231], v[20:23]
	v_mfma_f32_16x16x32_bf16 v[16:19], v[182:185], v[228:231], v[16:19]
	v_mfma_f32_16x16x32_bf16 v[0:3], v[182:185], v[236:239], v[0:3]
	v_mfma_f32_16x16x32_bf16 v[4:7], v[174:177], v[236:239], v[4:7]
	s_setprio 0
	s_barrier
; #define PG8_STAGE(bufoff, gbase, voff) do { _Pragma("unroll") for (int _i = 0; _i < 2; ++_i) \
;         __builtin_amdgcn_global_load_lds((const unsigned*)((const char*)(gbase) + (voff)[_i]), (PG8_LAS unsigned*)(lds + (bufoff) + ldsw + _i * 8192), 16, 0, 0); } while (0)
; #define PG8_LDA(dst, b, h) do { _Pragma("unroll") for (int m = 0; m < 4; ++m) _Pragma("unroll") for (int k = 0; k < 2; ++k) dst[m][k] = *(const PG8_LAS bf16x8*)(lds + PG8_SA(b, h) + aoff + m * 2048 + k * 1024); } while (0)
; #define PG8_LDB(dst, b, h) do { _Pragma("unroll") for (int n = 0; n < 2; ++n) _Pragma("unroll") for (int k = 0; k < 2; ++k) dst[n][k] = *(const PG8_LAS bf16x8*)(lds + PG8_SB(b, h) + boff + n * 2048 + k * 1024); } while (0)
; #define PG8_MMA(ai, bj, At, Bt) do { __builtin_amdgcn_s_setprio(1); _Pragma("unroll") for (int m = 0; m < 4; ++m) _Pragma("unroll") for (int n = 0; n < 2; ++n) _Pragma("unroll") for (int k = 0; k < 2; ++k) \
;         acc[ai][bj][m][n] = __builtin_amdgcn_mfma_f32_16x16x32_bf16(Bt[n][k], At[m][k], acc[ai][bj][m][n], 0, 0, 0); __builtin_amdgcn_s_setprio(0); } while (0)
; #define PG8_WAIT_V(n) asm volatile("s_waitcnt vmcnt(" #n ")" ::: "memory")
; #define PG8_WAIT_L(n) asm volatile("s_waitcnt lgkmcnt(" #n ")" ::: "memory")
; #define PG8_BAR __builtin_amdgcn_s_barrier()
; #define PG8_SCHED __builtin_amdgcn_sched_barrier(0)
; template <class Epi, class Sched, bool ALIGN_EPI = false, bool SP2 = false>
; __device__ __forceinline__ void gemm_phase(PG8_LAS unsigned char* lds, const Gemm g, const Sched& S, const Epi& E) {
;     ...
;             PG8_LDB(B0, 1, 0); PG8_LDB(B1, 1, 1); PG8_SCHED; PG8_LDA(At, 1, 0); PG8_STAGE(PG8_SA(0, 1), a2 + hstep, voffA);
;             PG8_WAIT_V(8); PG8_WAIT_L(0); PG8_BAR; PG8_MMA(0, 0, At, B0); PG8_MMA(0, 1, At, B1); PG8_BAR; PG8_SCHED;
;             PG8_LDA(At, 1, 1); PG8_STAGE(PG8_SB(1, 0), b3, voffB); PG8_STAGE(PG8_SB(1, 1), b3 + hstep, voffB); PG8_STAGE(PG8_SA(1, 0), a3, voffA);
;             PG8_WAIT_V(8); PG8_WAIT_L(0); PG8_BAR; PG8_MMA(1, 0, At, B0); PG8_MMA(1, 1, At, B1); PG8_BAR; PG8_SCHED;
	s_add_i32 s81, 0, 0x18000
	s_add_i32 s92, 0, 0x1c000
	v_add_u32_e32 v142, s81, v213
	v_add_u32_e32 v151, s92, v213
	s_add_u32 s42, s42, s30
	s_addc_u32 s43, s43, 0
	s_mov_b32 m0, s19
	v_lshl_add_u64 v[250:251], s[42:43], 0, v[146:147]
	global_load_lds_dwordx4 v[250:251], off
	v_lshl_add_u64 v[250:251], s[42:43], 0, v[148:149]
	s_mov_b32 m0, s20
	s_nop 0
	global_load_lds_dwordx4 v[250:251], off
	ds_read_b128 v[130:133], v142
	ds_read_b128 v[134:137], v142 offset:1024
	ds_read_b128 v[138:141], v142 offset:2048
	ds_read_b128 v[142:145], v142 offset:3072
	ds_read_b128 v[158:161], v151
	ds_read_b128 v[174:177], v151 offset:1024
	ds_read_b128 v[178:181], v151 offset:2048
	ds_read_b128 v[182:185], v151 offset:3072
	ds_read_b128 v[186:189], v214 offset:32768
	ds_read_b128 v[190:193], v214 offset:33792
	ds_read_b128 v[216:219], v214 offset:34816
	ds_read_b128 v[220:223], v214 offset:35840
	ds_read_b128 v[224:227], v214 offset:36864
	ds_read_b128 v[228:231], v214 offset:37888
	ds_read_b128 v[232:235], v214 offset:38912
	ds_read_b128 v[236:239], v214 offset:39936
	s_waitcnt vmcnt(8)
	s_waitcnt lgkmcnt(0)
	s_barrier
	s_setprio 1
	s_waitcnt lgkmcnt(0)
	v_mfma_f32_16x16x32_bf16 v[126:129], v[130:133], v[186:189], v[126:129]
	v_mfma_f32_16x16x32_bf16 v[122:125], v[138:141], v[186:189], v[122:125]
	v_mfma_f32_16x16x32_bf16 v[106:109], v[138:141], v[216:219], v[106:109]
	v_mfma_f32_16x16x32_bf16 v[110:113], v[130:133], v[216:219], v[110:113]
	v_mfma_f32_16x16x32_bf16 v[94:97], v[130:133], v[224:227], v[94:97]
	v_mfma_f32_16x16x32_bf16 v[90:93], v[138:141], v[224:227], v[90:93]
	v_mfma_f32_16x16x32_bf16 v[72:75], v[138:141], v[232:235], v[72:75]
	v_mfma_f32_16x16x32_bf16 v[76:79], v[130:133], v[232:235], v[76:79]
	v_mfma_f32_16x16x32_bf16 v[126:129], v[134:137], v[190:193], v[126:129]
	v_mfma_f32_16x16x32_bf16 v[122:125], v[142:145], v[190:193], v[122:125]
	v_mfma_f32_16x16x32_bf16 v[106:109], v[142:145], v[220:223], v[106:109]
	v_mfma_f32_16x16x32_bf16 v[110:113], v[134:137], v[220:223], v[110:113]
	v_mfma_f32_16x16x32_bf16 v[94:97], v[134:137], v[228:231], v[94:97]
	v_mfma_f32_16x16x32_bf16 v[90:93], v[142:145], v[228:231], v[90:93]
	v_mfma_f32_16x16x32_bf16 v[72:75], v[142:145], v[236:239], v[72:75]
	v_mfma_f32_16x16x32_bf16 v[76:79], v[134:137], v[236:239], v[76:79]
	v_mfma_f32_16x16x32_bf16 v[118:121], v[158:161], v[186:189], v[118:121]
	v_mfma_f32_16x16x32_bf16 v[114:117], v[178:181], v[186:189], v[114:117]
	v_mfma_f32_16x16x32_bf16 v[98:101], v[178:181], v[216:219], v[98:101]
	v_mfma_f32_16x16x32_bf16 v[102:105], v[158:161], v[216:219], v[102:105]
	v_mfma_f32_16x16x32_bf16 v[86:89], v[158:161], v[224:227], v[86:89]
	v_mfma_f32_16x16x32_bf16 v[82:85], v[178:181], v[224:227], v[82:85]
	v_mfma_f32_16x16x32_bf16 v[64:67], v[178:181], v[232:235], v[64:67]
	v_mfma_f32_16x16x32_bf16 v[68:71], v[158:161], v[232:235], v[68:71]
	v_mfma_f32_16x16x32_bf16 v[118:121], v[174:177], v[190:193], v[118:121]
	v_mfma_f32_16x16x32_bf16 v[114:117], v[182:185], v[190:193], v[114:117]
	v_mfma_f32_16x16x32_bf16 v[98:101], v[182:185], v[220:223], v[98:101]
	v_mfma_f32_16x16x32_bf16 v[102:105], v[174:177], v[220:223], v[102:105]
	v_mfma_f32_16x16x32_bf16 v[86:89], v[174:177], v[228:231], v[86:89]
	v_mfma_f32_16x16x32_bf16 v[82:85], v[182:185], v[228:231], v[82:85]
	v_mfma_f32_16x16x32_bf16 v[64:67], v[182:185], v[236:239], v[64:67]
	v_mfma_f32_16x16x32_bf16 v[68:71], v[174:177], v[236:239], v[68:71]
	s_setprio 0
	s_barrier
	s_add_i32 s42, s81, s16
	v_lshl_add_u64 v[194:195], v[194:195], 0, s[0:1]
	s_mov_b32 m0, s42
	s_nop 0
	global_load_lds_dwordx4 v[194:195], off
	v_lshl_add_u64 v[194:195], v[240:241], 0, s[0:1]
	s_add_i32 m0, s42, 0x2000
	s_add_i32 s42, s92, s16
	global_load_lds_dwordx4 v[194:195], off
	v_lshl_add_u64 v[194:195], v[242:243], 0, s[0:1]
	s_mov_b32 m0, s42
	s_nop 0
	global_load_lds_dwordx4 v[194:195], off
	v_lshl_add_u64 v[194:195], v[244:245], 0, s[0:1]
	s_add_i32 m0, s42, 0x2000
	s_nop 0
	global_load_lds_dwordx4 v[194:195], off
	v_lshl_add_u64 v[194:195], v[246:247], 0, s[0:1]
	s_mov_b32 m0, s8
	s_nop 0
	global_load_lds_dwordx4 v[194:195], off
	v_lshl_add_u64 v[194:195], v[248:249], 0, s[0:1]
	s_mov_b32 m0, s9
	s_nop 0
	global_load_lds_dwordx4 v[194:195], off
	ds_read_b128 v[186:189], v214 offset:49152
	ds_read_b128 v[190:193], v214 offset:50176
	ds_read_b128 v[216:219], v214 offset:51200
	ds_read_b128 v[220:223], v214 offset:52224
	ds_read_b128 v[224:227], v214 offset:53248
	ds_read_b128 v[228:231], v214 offset:54272
	ds_read_b128 v[232:235], v214 offset:55296
	ds_read_b128 v[236:239], v214 offset:56320
	s_waitcnt vmcnt(8)
	s_waitcnt lgkmcnt(0)
	s_barrier
	s_setprio 1
	s_waitcnt lgkmcnt(0)
	v_mfma_f32_16x16x32_bf16 v[60:63], v[130:133], v[186:189], v[60:63]
	v_mfma_f32_16x16x32_bf16 v[56:59], v[138:141], v[186:189], v[56:59]
	v_mfma_f32_16x16x32_bf16 v[40:43], v[138:141], v[216:219], v[40:43]
	v_mfma_f32_16x16x32_bf16 v[44:47], v[130:133], v[216:219], v[44:47]
	v_mfma_f32_16x16x32_bf16 v[28:31], v[130:133], v[224:227], v[28:31]
	v_mfma_f32_16x16x32_bf16 v[24:27], v[138:141], v[224:227], v[24:27]
	v_mfma_f32_16x16x32_bf16 v[8:11], v[138:141], v[232:235], v[8:11]
	v_mfma_f32_16x16x32_bf16 v[12:15], v[130:133], v[232:235], v[12:15]
	v_mfma_f32_16x16x32_bf16 v[60:63], v[134:137], v[190:193], v[60:63]
	v_mfma_f32_16x16x32_bf16 v[56:59], v[142:145], v[190:193], v[56:59]
	v_mfma_f32_16x16x32_bf16 v[40:43], v[142:145], v[220:223], v[40:43]
	v_mfma_f32_16x16x32_bf16 v[44:47], v[134:137], v[220:223], v[44:47]
	v_mfma_f32_16x16x32_bf16 v[28:31], v[134:137], v[228:231], v[28:31]
	v_mfma_f32_16x16x32_bf16 v[24:27], v[142:145], v[228:231], v[24:27]
	v_mfma_f32_16x16x32_bf16 v[8:11], v[142:145], v[236:239], v[8:11]
	v_mfma_f32_16x16x32_bf16 v[12:15], v[134:137], v[236:239], v[12:15]
	v_mfma_f32_16x16x32_bf16 v[52:55], v[158:161], v[186:189], v[52:55]
	v_mfma_f32_16x16x32_bf16 v[48:51], v[178:181], v[186:189], v[48:51]
	v_mfma_f32_16x16x32_bf16 v[32:35], v[178:181], v[216:219], v[32:35]
	v_mfma_f32_16x16x32_bf16 v[36:39], v[158:161], v[216:219], v[36:39]
	v_mfma_f32_16x16x32_bf16 v[20:23], v[158:161], v[224:227], v[20:23]
	v_mfma_f32_16x16x32_bf16 v[16:19], v[178:181], v[224:227], v[16:19]
	v_mfma_f32_16x16x32_bf16 v[0:3], v[178:181], v[232:235], v[0:3]
	v_mfma_f32_16x16x32_bf16 v[4:7], v[158:161], v[232:235], v[4:7]
	v_mfma_f32_16x16x32_bf16 v[52:55], v[174:177], v[190:193], v[52:55]
	v_mfma_f32_16x16x32_bf16 v[48:51], v[182:185], v[190:193], v[48:51]
	v_mfma_f32_16x16x32_bf16 v[32:35], v[182:185], v[220:223], v[32:35]
	v_mfma_f32_16x16x32_bf16 v[36:39], v[174:177], v[220:223], v[36:39]
	v_mfma_f32_16x16x32_bf16 v[20:23], v[174:177], v[228:231], v[20:23]
	v_mfma_f32_16x16x32_bf16 v[16:19], v[182:185], v[228:231], v[16:19]
	v_mfma_f32_16x16x32_bf16 v[0:3], v[182:185], v[236:239], v[0:3]
	v_mfma_f32_16x16x32_bf16 v[4:7], v[174:177], v[236:239], v[4:7]
	s_setprio 0
	s_barrier
	s_add_u32 s38, s38, 0x100
	s_addc_u32 s39, s39, 0
	s_add_u32 s41, s41, 0x100
	s_addc_u32 s45, s45, 0
	s_cmp_ge_u32 s71, s44
	s_mov_b32 s42, s71
	s_cbranch_scc0 .LBB0_647
